# attention loop: Q fragments held in registers, next tile K fragments read beside the PV MFMAs (K one more tile ahead in the ring), no LDS reads between the barrier and the first QK MFMA
# speedup vs baseline: 1.0343x; 1.0054x over previous
; #define SB() __builtin_amdgcn_sched_barrier(0)
; #define MF32(a,b,c) __builtin_amdgcn_mfma_f32_32x32x16_bf16(a,b,c,0,0,0)
; #define EXP1(x) x=__builtin_amdgcn_exp2f((x)-mh_)
; __device__ __forceinline__ bf16x8 vfrag(lds_cptr vp,int i){ const s16x4 lo=vtr(vp+(i&3)*4096+(i>>2)*1024), hh=vtr(vp+(i&3)*4096+(i>>2)*1024+512); return (bf16x8){lo[0],lo[1],lo[2],lo[3],hh[0],hh[1],hh[2],hh[3]}; }
; __device__ __forceinline__ u32x4 packw(const f32x16&p,int base){ u32x4 w; w[0]=cvtpk_s(p[base],p[base+1]); w[1]=cvtpk_s(p[base+2],p[base+3]); w[2]=cvtpk_s(p[base+4],p[base+5]); w[3]=cvtpk_s(p[base+6],p[base+7]); return w; }
; template<int THRL,bool FIRST> __device__ __forceinline__ void step_main(f32x16&p0,f32x16&p1,f32x16&n0,f32x16&n1,St&S,lds_cptr kpn,lds_cptr qp,lds_cptr vp,float*wsf,int r32,int hi,float&rm){
;     ...
;   bf16x8 ka=KF(0),kb=KF(1),kc=KF(2),kd=KF(3),qa=QF(0),qb=QF(1);
;   decide<THRL,FIRST>(rm,S,wsf,r32,hi);
;   u32x4 pw0,pw1,pw2,pw3; const float mh_=S.mhat; const f32x16 z=f32x16{};
;   SB();
;   n0=MF32(ka,qa,z); ka=KF(4); EXP1(p0[0]);EXP1(p0[1]);EXP1(p0[2]); SB();
;   n1=MF32(kb,qa,z); kb=KF(5); qa=QF(2); EXP1(p0[3]);EXP1(p0[4]);EXP1(p0[5]); SB();
;   n0=MF32(kc,qb,n0);   kc=KF(6); EXP1(p0[6]);EXP1(p0[7]);EXP1(p0[8]); SB();
;   n1=MF32(kd,qb,n1);   kd=KF(7); qb=QF(3); EXP1(p0[9]);EXP1(p0[10]);EXP1(p0[11]); SB();
;   bf16x8 vfa=vfrag(vp,0);
;   n0=MF32(ka,qa,n0);   EXP1(p0[12]);EXP1(p0[13]);EXP1(p0[14]); pw0=packw(p0,0); SB();
;   bf16x8 vfb=vfrag(vp,1);
;   n1=MF32(kb,qa,n1);   EXP1(p0[15]);EXP1(p1[0]);EXP1(p1[1]); SB();
;   bf16x8 vfc=vfrag(vp,2);
;   n0=MF32(kc,qb,n0);   EXP1(p1[2]);EXP1(p1[3]);EXP1(p1[4]); pw1=packw(p0,8); SB();
;   bf16x8 vfd=vfrag(vp,3);
;   n1=MF32(kd,qb,n1);   EXP1(p1[5]);EXP1(p1[6]);EXP1(p1[7]); SB();
;     ...
;   float sa=p0[0]+p0[1];
;     ...
;   PVG(0,pw0,vfa,4, p0[2],p0[3],p0[4],p0[5],   do{EXP1(p1[8]);EXP1(p1[9]);}while(0));
;   PVG(1,pw0,vfb,5, p0[6],p0[7],p0[8],p0[9], do{EXP1(p1[10]);EXP1(p1[11]);}while(0));
;   PVG(2,pw0,vfc,6, p0[10],p0[11],p0[12],p0[13], do{EXP1(p1[12]);EXP1(p1[13]);}while(0));
;   PVG(3,pw0,vfd,7, p0[14],p0[15],p1[0],p1[1],   do{EXP1(p1[14]);EXP1(p1[15]);}while(0));
;   PVG(4,pw1,vfa,8, p1[2],p1[3],p1[4],p1[5],   pw2=packw(p1,0));
;   PVG(5,pw1,vfb,9, p1[6],p1[7],p1[8],p1[9], pw3=packw(p1,8));
;   PVG(6,pw1,vfc,10, p1[10],p1[11],p1[12],p1[13], do{}while(0));
;   PVG(7,pw1,vfd,11, p1[14],p1[15],0.f,0.f, do{}while(0));
.LBB0_275:
	s_waitcnt lgkmcnt(1)
	v_mfma_f32_32x32x16_bf16 v[98:113], v[218:221], v[214:217], 0
	ds_read_b128 v[178:181], v249 offset:20480
	v_sub_f32_e32 v82, v131, v247
	v_sub_f32_e32 v17, v130, v247
	v_exp_f32_e32 v190, v82
	v_sub_f32_e32 v82, v132, v247
	v_exp_f32_e32 v17, v17
	v_exp_f32_e32 v191, v82
	v_sub_f32_e32 v82, v133, v247
	v_exp_f32_e32 v192, v82
	v_sub_f32_e32 v82, v134, v247
	v_exp_f32_e32 v193, v82
	v_sub_f32_e32 v82, v135, v247
	v_exp_f32_e32 v194, v82
	v_mfma_f32_32x32x16_bf16 v[82:97], v[210:213], v[214:217], 0
	ds_read_b128 v[182:185], v249 offset:20992
	ds_read_b128 v[186:189], v248 offset:2048
	s_waitcnt lgkmcnt(3)
	v_mfma_f32_32x32x16_bf16 v[98:113], v[12:15], v[8:11], v[98:113]
	ds_read_b128 v[130:133], v249 offset:22528
	v_sub_f32_e32 v134, v136, v247
	v_exp_f32_e32 v195, v134
	v_sub_f32_e32 v134, v137, v247
	v_exp_f32_e32 v196, v134
	v_sub_f32_e32 v134, v138, v247
	v_exp_f32_e32 v197, v134
	v_mfma_f32_32x32x16_bf16 v[82:97], v[4:7], v[8:11], v[82:97]
	ds_read_b128 v[12:15], v249 offset:23040
	ds_read_b128 v[134:137], v248 offset:3072
	v_sub_f32_e32 v138, v139, v247
	v_exp_f32_e32 v198, v138
	v_sub_f32_e32 v138, v140, v247
	v_exp_f32_e32 v199, v138
	v_sub_f32_e32 v138, v141, v247
	v_exp_f32_e32 v200, v138
	s_waitcnt lgkmcnt(3)
	v_mfma_f32_32x32x16_bf16 v[98:113], v[178:181], v[186:189], v[98:113]
	ds_read_b64_tr_b16 v[4:5], v246 offset:40960
	ds_read_b64_tr_b16 v[6:7], v246 offset:41472
	v_sub_f32_e32 v8, v142, v247
	v_exp_f32_e32 v201, v8
	v_sub_f32_e32 v8, v143, v247
	v_exp_f32_e32 v202, v8
	v_sub_f32_e32 v8, v144, v247
	v_exp_f32_e32 v179, v8
	v_cvt_pk_bf16_f32 v8, v17, v190
	v_cvt_pk_bf16_f32 v9, v191, v192
	v_cvt_pk_bf16_f32 v10, v193, v194
	v_cvt_pk_bf16_f32 v11, v195, v196
	v_mfma_f32_32x32x16_bf16 v[82:97], v[182:185], v[186:189], v[82:97]
	ds_read_b64_tr_b16 v[138:139], v246 offset:45056
	ds_read_b64_tr_b16 v[140:141], v246 offset:45568
	v_sub_f32_e32 v114, v114, v247
	v_sub_f32_e32 v142, v145, v247
	v_exp_f32_e32 v181, v114
	v_sub_f32_e32 v114, v115, v247
	v_exp_f32_e32 v180, v142
	v_exp_f32_e32 v203, v114
	s_waitcnt lgkmcnt(4)
	v_mfma_f32_32x32x16_bf16 v[98:113], v[130:133], v[134:137], v[98:113]
	ds_read_b64_tr_b16 v[142:143], v246 offset:49152
	ds_read_b64_tr_b16 v[144:145], v246 offset:49664
	v_sub_f32_e32 v114, v116, v247
	v_exp_f32_e32 v182, v114
	v_sub_f32_e32 v114, v117, v247
	v_exp_f32_e32 v183, v114
	v_sub_f32_e32 v114, v118, v247
	v_exp_f32_e32 v184, v114
	v_cvt_pk_bf16_f32 v114, v197, v198
	v_cvt_pk_bf16_f32 v115, v199, v200
	v_cvt_pk_bf16_f32 v116, v201, v202
	v_cvt_pk_bf16_f32 v117, v179, v180
	v_mfma_f32_32x32x16_bf16 v[82:97], v[12:15], v[134:137], v[82:97]
	ds_read_b64_tr_b16 v[130:131], v246 offset:53248
	ds_read_b64_tr_b16 v[132:133], v246 offset:53760
	v_sub_f32_e32 v118, v119, v247
	v_exp_f32_e32 v185, v118
	v_sub_f32_e32 v118, v120, v247
	v_exp_f32_e32 v186, v118
	v_sub_f32_e32 v118, v121, v247
	v_exp_f32_e32 v187, v118
	s_waitcnt lgkmcnt(6)
	v_mfma_f32_32x32x16_bf16 v[18:33], v[8:11], v[4:7], v[18:33]
	ds_read_b64_tr_b16 v[12:13], v246 offset:41984
	ds_read_b64_tr_b16 v[14:15], v246 offset:42496
	v_sub_f32_e32 v118, v122, v247
	v_exp_f32_e32 v134, v118
	v_sub_f32_e32 v118, v123, v247
	v_exp_f32_e32 v135, v118
	s_waitcnt lgkmcnt(6)
	v_mfma_f32_32x32x16_bf16 v[34:49], v[8:11], v[138:141], v[34:49]
	ds_read_b64_tr_b16 v[4:5], v246 offset:46080
	ds_read_b64_tr_b16 v[6:7], v246 offset:46592
	v_sub_f32_e32 v118, v124, v247
	v_exp_f32_e32 v136, v118
	v_sub_f32_e32 v118, v125, v247
	v_exp_f32_e32 v137, v118
	s_waitcnt lgkmcnt(6)
	v_mfma_f32_32x32x16_bf16 v[50:65], v[8:11], v[142:145], v[50:65]
	ds_read_b64_tr_b16 v[118:119], v246 offset:50176
	ds_read_b64_tr_b16 v[120:121], v246 offset:50688
	v_sub_f32_e32 v122, v126, v247
	v_exp_f32_e32 v138, v122
	v_sub_f32_e32 v122, v127, v247
	v_exp_f32_e32 v139, v122
	s_waitcnt lgkmcnt(6)
	v_mfma_f32_32x32x16_bf16 v[66:81], v[8:11], v[130:133], v[66:81]
	ds_read_b64_tr_b16 v[122:123], v246 offset:54272
	ds_read_b64_tr_b16 v[124:125], v246 offset:54784
	v_sub_f32_e32 v126, v128, v247
	v_exp_f32_e32 v140, v126
	v_sub_f32_e32 v126, v129, v247
	v_exp_f32_e32 v141, v126
	s_waitcnt lgkmcnt(6)
	v_mfma_f32_32x32x16_bf16 v[18:33], v[114:117], v[12:15], v[18:33]
	ds_read_b64_tr_b16 v[8:9], v246 offset:43008
	ds_read_b64_tr_b16 v[10:11], v246 offset:43520
	v_cvt_pk_bf16_f32 v126, v181, v203
	v_cvt_pk_bf16_f32 v127, v182, v183
	v_cvt_pk_bf16_f32 v128, v184, v185
	v_cvt_pk_bf16_f32 v129, v186, v187
	s_waitcnt lgkmcnt(6)
	v_mfma_f32_32x32x16_bf16 v[34:49], v[114:117], v[4:7], v[34:49]
	ds_read_b64_tr_b16 v[12:13], v246 offset:47104
	ds_read_b64_tr_b16 v[14:15], v246 offset:47616
	v_cvt_pk_bf16_f32 v130, v134, v135
	v_cvt_pk_bf16_f32 v131, v136, v137
	v_cvt_pk_bf16_f32 v132, v138, v139
	v_cvt_pk_bf16_f32 v133, v140, v141
	s_waitcnt lgkmcnt(6)
	v_mfma_f32_32x32x16_bf16 v[50:65], v[114:117], v[118:121], v[50:65]
	ds_read_b64_tr_b16 v[4:5], v246 offset:51200
	ds_read_b64_tr_b16 v[6:7], v246 offset:51712
	s_waitcnt lgkmcnt(6)
	v_mfma_f32_32x32x16_bf16 v[66:81], v[114:117], v[122:125], v[66:81]
	ds_read_b64_tr_b16 v[118:119], v246 offset:55296
	ds_read_b64_tr_b16 v[120:121], v246 offset:55808
	s_waitcnt lgkmcnt(6)
; __device__ __forceinline__ float max3f(float a,float b,float c){float r;asm("v_max3_f32 %0, %1, %2, %3":"=v"(r):"v"(a),"v"(b),"v"(c));return r;}
; __device__ __forceinline__ float max2f(float a,float b){float r;asm("v_max_f32_e32 %0, %1, %2":"=v"(r):"v"(a),"v"(b));return r;}
; #define A128_WAITBAR() asm volatile("s_waitcnt vmcnt(0) lgkmcnt(0)\n\ts_barrier":::"memory")
;   #define PINAB() asm volatile("":"+v"(ma),"+v"(mb))
;   #define DMA_K(t,so) glds16s((const char*)K+(size_t)(t)*(64*PIN*2),koff,(unsigned)__builtin_amdgcn_readfirstlane(kdst+(so)))
; template<int THRL,bool FIRST> __device__ __forceinline__ void step_main(f32x16&p0,f32x16&p1,f32x16&n0,f32x16&n1,St&S,lds_cptr kpn,lds_cptr qp,lds_cptr vp,float*wsf,int r32,int hi,float&rm){
;     ...
;   float ma,mb;
;     ...
;   PVG(8,pw2,vfa,12,0.f,0.f,0.f,0.f, do{ma=max3f(n0[0],n0[1],n1[0]);mb=max3f(n0[2],n0[3],n1[1]);PINAB();}while(0));
;   PVG(9,pw2,vfb,13,0.f,0.f,0.f,0.f, do{ma=max3f(ma,n1[2],n1[3]);mb=max3f(mb,n0[4],n0[5]);PINAB();}while(0));
;   PVG(10,pw2,vfc,14,0.f,0.f,0.f,0.f, do{ma=max3f(ma,n0[6],n0[7]);mb=max3f(mb,n1[4],n1[5]);PINAB();}while(0));
;   PVG(11,pw2,vfd,15,0.f,0.f,0.f,0.f, do{ma=max3f(ma,n1[6],n1[7]);mb=max3f(mb,n0[8],n0[9]);PINAB();}while(0));
;   PVG(12,pw3,vfa,16,0.f,0.f,0.f,0.f, do{ma=max3f(ma,n0[10],n0[11]);mb=max3f(mb,n1[8],n1[9]);PINAB();}while(0));
;   PVG(13,pw3,vfb,16,0.f,0.f,0.f,0.f, do{ma=max3f(ma,n1[10],n1[11]);mb=max3f(mb,n0[12],n0[13]);PINAB();}while(0));
;   PVG(14,pw3,vfc,16,0.f,0.f,0.f,0.f, do{ma=max3f(ma,n0[14],n0[15]);mb=max3f(mb,n1[12],n1[13]);PINAB();}while(0));
;   PVG(15,pw3,vfd,16,0.f,0.f,0.f,0.f, do{ma=max3f(ma,n1[14],n1[15]);ma=max2f(ma,mb);PINAB();}while(0));
;     ...
;   { auto rr=__builtin_amdgcn_permlane32_swap(__float_as_uint(ma),__float_as_uint(ma),false,false); rm=max2f(__uint_as_float(rr[0]),__uint_as_float(rr[1])); }
;     ...
;   S.l_reg+=sa;
; template<int THRL> __device__ __forceinline__ void unit(int qb,const bf16*Q,const bf16*K,const bf16*V,bf16*O,char*shm){
;     ...
;     step_main<THRL,true>(pA0,pA1,pB0,pB1,S,kp0+ks1,qp,vp0,wsf,r32,hi,rm); A128_WAITBAR(); ROT();
;     DMA_K(3,ks2); DMA_V(2,0);
;     step_main<THRL,false>(pB0,pB1,pA0,pA1,S,kp0+ks1,qp,vp0+VBUF,wsf,r32,hi,rm); A128_WAITBAR(); ROT();
;     for(t=2;t<NT-4;t+=2){
;       DMA_K(t+2,ks2); DMA_V(t+1,VBUF);
;       step_main<THRL,false>(pA0,pA1,pB0,pB1,S,kp0+ks1,qp,vp0,wsf,r32,hi,rm); A128_WAITBAR(); ROT();
	v_mfma_f32_32x32x16_bf16 v[18:33], v[126:129], v[8:11], v[18:33]
	ds_read_b64_tr_b16 v[114:115], v246 offset:44032
	ds_read_b64_tr_b16 v[116:117], v246 offset:44544
	v_max3_f32 v122, v98, v99, v82
	v_max3_f32 v123, v100, v101, v83
	s_nop 0
	s_waitcnt lgkmcnt(6)
	v_mfma_f32_32x32x16_bf16 v[34:49], v[126:129], v[12:15], v[34:49]
	ds_read_b64_tr_b16 v[8:9], v246 offset:48128
	ds_read_b64_tr_b16 v[10:11], v246 offset:48640
	v_max3_f32 v122, v122, v84, v85
	v_max3_f32 v123, v123, v102, v103
	s_nop 0
	s_waitcnt lgkmcnt(6)
	v_mfma_f32_32x32x16_bf16 v[50:65], v[126:129], v[4:7], v[50:65]
	ds_read_b64_tr_b16 v[12:13], v246 offset:52224
	ds_read_b64_tr_b16 v[14:15], v246 offset:52736
	v_max3_f32 v122, v122, v104, v105
	v_max3_f32 v123, v123, v86, v87
	s_nop 0
	s_waitcnt lgkmcnt(6)
	v_mfma_f32_32x32x16_bf16 v[66:81], v[126:129], v[118:121], v[66:81]
	ds_read_b64_tr_b16 v[4:5], v246 offset:56320
	ds_read_b64_tr_b16 v[6:7], v246 offset:56832
	v_max3_f32 v122, v122, v88, v89
	v_max3_f32 v123, v123, v106, v107
	s_nop 0
	s_waitcnt lgkmcnt(6)
	v_mfma_f32_32x32x16_bf16 v[18:33], v[130:133], v[114:117], v[18:33]
	v_max3_f32 v118, v122, v108, v109
	v_max3_f32 v119, v123, v90, v91
	s_nop 0
	s_waitcnt lgkmcnt(4)
	v_mfma_f32_32x32x16_bf16 v[34:49], v[130:133], v[8:11], v[34:49]
	v_max3_f32 v114, v118, v92, v93
	v_max3_f32 v115, v119, v110, v111
	s_nop 0
	s_waitcnt lgkmcnt(2)
	v_mfma_f32_32x32x16_bf16 v[50:65], v[130:133], v[12:15], v[50:65]
	v_max3_f32 v8, v114, v112, v113
	v_max3_f32 v9, v115, v94, v95
	s_nop 0
	s_waitcnt lgkmcnt(0)
	v_mfma_f32_32x32x16_bf16 v[66:81], v[130:133], v[4:7], v[66:81]
	v_max3_f32 v8, v8, v96, v97
	s_nop 0
	v_max_f32_e32 v8, v8, v9
	s_nop 0
	s_nop 0
	v_mov_b32_e32 v4, v8
	s_nop 1
	v_permlane32_swap_b32_e32 v8, v4
	v_max_f32_e32 v178, v8, v4
	v_add_f32_e32 v4, v17, v190
	v_add_f32_e32 v4, v191, v4
	v_add_f32_e32 v4, v192, v4
	v_add_f32_e32 v4, v193, v4
	v_add_f32_e32 v4, v194, v4
	v_add_f32_e32 v4, v195, v4
	v_add_f32_e32 v4, v196, v4
	v_add_f32_e32 v4, v197, v4
	v_add_f32_e32 v4, v198, v4
	v_add_f32_e32 v4, v199, v4
	v_add_f32_e32 v4, v200, v4
	v_add_f32_e32 v4, v201, v4
	v_add_f32_e32 v4, v202, v4
	v_add_f32_e32 v4, v179, v4
	v_add_f32_e32 v4, v180, v4
	v_add_f32_e32 v4, v181, v4
	v_add_f32_e32 v4, v203, v4
	v_add_f32_e32 v4, v182, v4
	v_add_f32_e32 v4, v183, v4
	v_add_f32_e32 v4, v184, v4
	v_add_f32_e32 v4, v185, v4
	v_add_f32_e32 v4, v186, v4
	v_add_f32_e32 v4, v187, v4
	v_add_f32_e32 v4, v134, v4
	v_add_f32_e32 v4, v135, v4
	v_add_f32_e32 v4, v136, v4
	v_add_f32_e32 v4, v137, v4
	v_add_f32_e32 v4, v138, v4
	v_add_f32_e32 v4, v139, v4
	v_add_f32_e32 v4, v140, v4
	s_waitcnt vmcnt(0) lgkmcnt(0)
	s_barrier
	v_add_f32_e32 v4, v141, v4
	v_add_f32_e32 v4, 0, v4
	s_add_i32 s89, s85, -4
	v_add_f32_e32 v251, v16, v4
	v_cmp_gt_u32_e64 s[6:7], 32, v243
	s_mov_b32 s90, 2
	v_lshl_add_u32 v16, v242, 2, s78
	s_movk_i32 s88, 0x2000
	s_mov_b32 s91, 0
	s_mov_b64 s[50:51], s[30:31]
	s_mov_b64 s[58:59], s[28:29]
	v_sub_f32_e32 v146, 0, v247
	v_sub_f32_e32 v147, 0, v247
	v_sub_f32_e32 v148, 0, v247
	v_sub_f32_e32 v149, 0, v247
	v_sub_f32_e32 v150, 0, v247
	v_sub_f32_e32 v151, 0, v247
	v_sub_f32_e32 v152, 0, v247
	v_sub_f32_e32 v153, 0, v247
	v_sub_f32_e32 v154, 0, v247
	v_sub_f32_e32 v155, 0, v247
	v_sub_f32_e32 v156, 0, v247
	v_sub_f32_e32 v157, 0, v247
	v_sub_f32_e32 v158, 0, v247
	v_sub_f32_e32 v159, 0, v247
	v_sub_f32_e32 v160, 0, v247
	v_sub_f32_e32 v161, 0, v247
	v_sub_f32_e32 v82, v82, v247
	v_sub_f32_e32 v83, v83, v247
	v_sub_f32_e32 v84, v84, v247
	v_sub_f32_e32 v85, v85, v247
	v_sub_f32_e32 v86, v86, v247
	v_sub_f32_e32 v87, v87, v247
	v_sub_f32_e32 v88, v88, v247
	v_sub_f32_e32 v89, v89, v247
	v_sub_f32_e32 v90, v90, v247
	v_sub_f32_e32 v91, v91, v247
	v_sub_f32_e32 v92, v92, v247
	v_sub_f32_e32 v93, v93, v247
	v_sub_f32_e32 v94, v94, v247
	v_sub_f32_e32 v95, v95, v247
	v_sub_f32_e32 v96, v96, v247
	v_sub_f32_e32 v97, v97, v247
	v_sub_f32_e32 v98, v98, v247
	v_sub_f32_e32 v99, v99, v247
	v_sub_f32_e32 v100, v100, v247
	v_sub_f32_e32 v101, v101, v247
	v_sub_f32_e32 v102, v102, v247
	v_sub_f32_e32 v103, v103, v247
	v_sub_f32_e32 v104, v104, v247
	v_sub_f32_e32 v105, v105, v247
	v_sub_f32_e32 v106, v106, v247
	v_sub_f32_e32 v107, v107, v247
	v_sub_f32_e32 v108, v108, v247
	v_sub_f32_e32 v109, v109, v247
	v_sub_f32_e32 v110, v110, v247
	v_sub_f32_e32 v111, v111, v247
	v_sub_f32_e32 v112, v112, v247
	v_sub_f32_e32 v113, v113, v247
	v_sub_f32_e32 v178, v178, v247
	s_add_u32 s60, s58, 0xfff40000
	s_addc_u32 s61, s59, -1
	s_add_i32 s4, s88, s84
	s_mov_b32 s5, m0
	s_mov_b32 m0, s4
	s_nop 0
	global_load_lds_dwordx4 v252, s[60:61]
	s_mov_b32 m0, s5
	ds_read_b128 v[164:167], v248
	ds_read_b128 v[168:171], v248 offset:1024
	ds_read_b128 v[172:175], v248 offset:2048
	ds_read_b128 v[236:239], v248 offset:3072
	v_add_u32_e32 v240, s91, v249
	ds_read_b128 v[204:207], v240
	ds_read_b128 v[208:211], v240 offset:512
	ds_read_b128 v[212:215], v240 offset:2048
	ds_read_b128 v[216:219], v240 offset:2560
	ds_read_b128 v[220:223], v240 offset:4096
	ds_read_b128 v[224:227], v240 offset:4608
	ds_read_b128 v[228:231], v240 offset:6144
	ds_read_b128 v[232:235], v240 offset:6656
	s_waitcnt vmcnt(0) lgkmcnt(0)
	s_barrier
	s_branch .LBB0_278

; #define SB() __builtin_amdgcn_sched_barrier(0)
; #define MF32(a,b,c) __builtin_amdgcn_mfma_f32_32x32x16_bf16(a,b,c,0,0,0)
; #define EXP1(x) x=__builtin_amdgcn_exp2f((x)-mh_)
; __device__ __forceinline__ bf16x8 vfrag(lds_cptr vp,int i){ const s16x4 lo=vtr(vp+(i&3)*4096+(i>>2)*1024), hh=vtr(vp+(i&3)*4096+(i>>2)*1024+512); return (bf16x8){lo[0],lo[1],lo[2],lo[3],hh[0],hh[1],hh[2],hh[3]}; }
; __device__ __forceinline__ u32x4 packw(const f32x16&p,int base){ u32x4 w; w[0]=cvtpk_s(p[base],p[base+1]); w[1]=cvtpk_s(p[base+2],p[base+3]); w[2]=cvtpk_s(p[base+4],p[base+5]); w[3]=cvtpk_s(p[base+6],p[base+7]); return w; }
; template<int THRL,bool FIRST> __device__ __forceinline__ void step_main(f32x16&p0,f32x16&p1,f32x16&n0,f32x16&n1,St&S,lds_cptr kpn,lds_cptr qp,lds_cptr vp,float*wsf,int r32,int hi,float&rm){
;     ...
;   bf16x8 ka=KF(0),kb=KF(1),kc=KF(2),kd=KF(3),qa=QF(0),qb=QF(1);
;   decide<THRL,FIRST>(rm,S,wsf,r32,hi);
;   u32x4 pw0,pw1,pw2,pw3; const float mh_=S.mhat; const f32x16 z=f32x16{};
;   SB();
;   n0=MF32(ka,qa,z); ka=KF(4); EXP1(p0[0]);EXP1(p0[1]);EXP1(p0[2]); SB();
;   n1=MF32(kb,qa,z); kb=KF(5); qa=QF(2); EXP1(p0[3]);EXP1(p0[4]);EXP1(p0[5]); SB();
;   n0=MF32(kc,qb,n0);   kc=KF(6); EXP1(p0[6]);EXP1(p0[7]);EXP1(p0[8]); SB();
;   n1=MF32(kd,qb,n1);   kd=KF(7); qb=QF(3); EXP1(p0[9]);EXP1(p0[10]);EXP1(p0[11]); SB();
;   bf16x8 vfa=vfrag(vp,0);
;   n0=MF32(ka,qa,n0);   EXP1(p0[12]);EXP1(p0[13]);EXP1(p0[14]); pw0=packw(p0,0); SB();
;   bf16x8 vfb=vfrag(vp,1);
;   n1=MF32(kb,qa,n1);   EXP1(p0[15]);EXP1(p1[0]);EXP1(p1[1]); SB();
;   bf16x8 vfc=vfrag(vp,2);
;   n0=MF32(kc,qb,n0);   EXP1(p1[2]);EXP1(p1[3]);EXP1(p1[4]); pw1=packw(p0,8); SB();
;   bf16x8 vfd=vfrag(vp,3);
;   n1=MF32(kd,qb,n1);   EXP1(p1[5]);EXP1(p1[6]);EXP1(p1[7]); SB();
;     ...
;   float sa=p0[0]+p0[1];
;     ...
;   PVG(0,pw0,vfa,4, p0[2],p0[3],p0[4],p0[5],   do{EXP1(p1[8]);EXP1(p1[9]);}while(0));
;   PVG(1,pw0,vfb,5, p0[6],p0[7],p0[8],p0[9], do{EXP1(p1[10]);EXP1(p1[11]);}while(0));
;   PVG(2,pw0,vfc,6, p0[10],p0[11],p0[12],p0[13], do{EXP1(p1[12]);EXP1(p1[13]);}while(0));
;   PVG(3,pw0,vfd,7, p0[14],p0[15],p1[0],p1[1],   do{EXP1(p1[14]);EXP1(p1[15]);}while(0));
;   PVG(4,pw1,vfa,8, p1[2],p1[3],p1[4],p1[5],   pw2=packw(p1,0));
;   PVG(5,pw1,vfb,9, p1[6],p1[7],p1[8],p1[9], pw3=packw(p1,8));
;   PVG(6,pw1,vfc,10, p1[10],p1[11],p1[12],p1[13], do{}while(0));
;   PVG(7,pw1,vfd,11, p1[14],p1[15],0.f,0.f, do{}while(0));
.LBB0_277:
	s_add_i32 s4, s91, 0x2000
	s_cmpk_lg_i32 s91, 0x4000
	s_cselect_b32 s88, s4, 0
	s_add_i32 s90, s90, 2
	v_mfma_f32_32x32x16_bf16 v[98:113], v[204:207], v[164:167], v[146:161]
	s_add_i32 s4, s88, s84
	s_add_u32 s60, s58, 0xc0000
	s_addc_u32 s61, s59, 0
	s_mov_b32 s5, m0
	s_mov_b32 m0, s4
	s_nop 0
	global_load_lds_dwordx4 v252, s[60:61]
	s_mov_b32 m0, s5
	v_exp_f32_e32 v130, v130
	v_exp_f32_e32 v131, v131
	v_exp_f32_e32 v132, v132
	v_exp_f32_e32 v133, v133
	v_exp_f32_e32 v134, v134
	v_exp_f32_e32 v135, v135
	v_mfma_f32_32x32x16_bf16 v[82:97], v[208:211], v[164:167], v[146:161]
	s_add_u32 s60, s50, 0xc0000
	s_addc_u32 s61, s51, 0
	s_mov_b32 s4, m0
	s_mov_b32 m0, s80
	s_nop 0
	global_load_lds_dwordx4 v250, s[60:61]
	s_mov_b32 m0, s4
	v_mfma_f32_32x32x16_bf16 v[98:113], v[212:215], v[168:171], v[98:113]
	s_add_u32 s60, s50, 0xc0080
	s_addc_u32 s61, s51, 0
	s_mov_b32 s4, m0
	s_mov_b32 m0, s83
	s_nop 0
	global_load_lds_dwordx4 v250, s[60:61]
	s_mov_b32 m0, s4
	v_exp_f32_e32 v136, v136
	v_exp_f32_e32 v137, v137
	v_exp_f32_e32 v138, v138
	v_mfma_f32_32x32x16_bf16 v[82:97], v[216:219], v[168:171], v[82:97]
	v_exp_f32_e32 v139, v139
	v_exp_f32_e32 v140, v140
	v_exp_f32_e32 v141, v141
	v_mfma_f32_32x32x16_bf16 v[98:113], v[220:223], v[172:175], v[98:113]
	v_exp_f32_e32 v142, v142
	ds_read_b64_tr_b16 v[4:5], v246 offset:40960
	ds_read_b64_tr_b16 v[6:7], v246 offset:41472
	v_exp_f32_e32 v143, v143
	v_exp_f32_e32 v144, v144
	v_cvt_pk_bf16_f32 v8, v130, v131
	v_cvt_pk_bf16_f32 v9, v132, v133
	v_cvt_pk_bf16_f32 v10, v134, v135
	v_cvt_pk_bf16_f32 v11, v136, v137
	v_mfma_f32_32x32x16_bf16 v[82:97], v[224:227], v[172:175], v[82:97]
	ds_read_b64_tr_b16 v[178:179], v246 offset:45056
	ds_read_b64_tr_b16 v[180:181], v246 offset:45568
	v_exp_f32_e32 v145, v145
	v_exp_f32_e32 v114, v114
	v_exp_f32_e32 v115, v115
	v_mfma_f32_32x32x16_bf16 v[98:113], v[228:231], v[236:239], v[98:113]
	ds_read_b64_tr_b16 v[182:183], v246 offset:49152
	ds_read_b64_tr_b16 v[184:185], v246 offset:49664
	v_exp_f32_e32 v116, v116
	v_exp_f32_e32 v117, v117
	v_exp_f32_e32 v118, v118
	v_cvt_pk_bf16_f32 v186, v138, v139
	v_cvt_pk_bf16_f32 v187, v140, v141
	v_cvt_pk_bf16_f32 v188, v142, v143
	v_cvt_pk_bf16_f32 v189, v144, v145
	v_mfma_f32_32x32x16_bf16 v[82:97], v[232:235], v[236:239], v[82:97]
	v_add_u32_e32 v240, s91, v249
	ds_read_b64_tr_b16 v[190:191], v246 offset:53248
	ds_read_b64_tr_b16 v[192:193], v246 offset:53760
	v_exp_f32_e32 v119, v119
	v_exp_f32_e32 v120, v120
	v_exp_f32_e32 v121, v121
	s_waitcnt lgkmcnt(6)
	v_mfma_f32_32x32x16_bf16 v[18:33], v[8:11], v[4:7], v[18:33]
	ds_read_b64_tr_b16 v[12:13], v246 offset:41984
	ds_read_b64_tr_b16 v[14:15], v246 offset:42496
	ds_read_b128 v[204:207], v240
	v_add_f32_e32 v194, v130, v131
	v_exp_f32_e32 v122, v122
	v_exp_f32_e32 v123, v123
	v_add_f32_e32 v194, v132, v194
	v_add_f32_e32 v4, v133, v194
	v_add_f32_e32 v4, v134, v4
	v_add_f32_e32 v194, v135, v4
	s_waitcnt lgkmcnt(7)
	v_mfma_f32_32x32x16_bf16 v[34:49], v[8:11], v[178:181], v[34:49]
	ds_read_b64_tr_b16 v[4:5], v246 offset:46080
	ds_read_b64_tr_b16 v[6:7], v246 offset:46592
	ds_read_b128 v[208:211], v240 offset:512
	v_exp_f32_e32 v124, v124
	v_exp_f32_e32 v125, v125
	v_add_f32_e32 v194, v136, v194
	v_add_f32_e32 v178, v137, v194
	v_add_f32_e32 v178, v138, v178
	v_add_f32_e32 v194, v139, v178
	s_waitcnt lgkmcnt(8)
	v_mfma_f32_32x32x16_bf16 v[50:65], v[8:11], v[182:185], v[50:65]
	ds_read_b64_tr_b16 v[178:179], v246 offset:50176
	ds_read_b64_tr_b16 v[180:181], v246 offset:50688
	ds_read_b128 v[212:215], v240 offset:2048
	v_exp_f32_e32 v126, v126
	v_exp_f32_e32 v127, v127
	v_add_f32_e32 v194, v140, v194
	v_add_f32_e32 v182, v141, v194
	v_add_f32_e32 v182, v142, v182
	v_add_f32_e32 v194, v143, v182
	s_waitcnt lgkmcnt(9)
	v_mfma_f32_32x32x16_bf16 v[66:81], v[8:11], v[190:193], v[66:81]
	ds_read_b64_tr_b16 v[182:183], v246 offset:54272
	ds_read_b64_tr_b16 v[184:185], v246 offset:54784
	ds_read_b128 v[216:219], v240 offset:2560
	v_exp_f32_e32 v128, v128
	v_exp_f32_e32 v129, v129
	v_add_f32_e32 v194, v144, v194
	v_add_f32_e32 v8, v145, v194
	v_add_f32_e32 v8, v114, v8
	v_add_f32_e32 v190, v115, v8
	s_waitcnt lgkmcnt(10)
	v_mfma_f32_32x32x16_bf16 v[18:33], v[186:189], v[12:15], v[18:33]
	ds_read_b64_tr_b16 v[8:9], v246 offset:43008
	ds_read_b64_tr_b16 v[10:11], v246 offset:43520
	ds_read_b128 v[220:223], v240 offset:4096
	v_add_f32_e32 v190, v116, v190
	v_add_f32_e32 v190, v117, v190
	v_add_f32_e32 v190, v118, v190
	v_add_f32_e32 v194, v119, v190
	v_cvt_pk_bf16_f32 v12, v114, v115
	v_cvt_pk_bf16_f32 v13, v116, v117
	v_cvt_pk_bf16_f32 v14, v118, v119
	v_cvt_pk_bf16_f32 v15, v120, v121
	s_waitcnt lgkmcnt(10)
	v_mfma_f32_32x32x16_bf16 v[34:49], v[186:189], v[4:7], v[34:49]
	ds_read_b64_tr_b16 v[190:191], v246 offset:47104
	ds_read_b64_tr_b16 v[192:193], v246 offset:47616
	ds_read_b128 v[224:227], v240 offset:4608
	v_add_f32_e32 v194, v120, v194
	v_add_f32_e32 v194, v121, v194
	v_add_f32_e32 v194, v122, v194
	v_add_f32_e32 v198, v123, v194
	v_cvt_pk_bf16_f32 v4, v122, v123
	v_cvt_pk_bf16_f32 v5, v124, v125
	v_cvt_pk_bf16_f32 v6, v126, v127
	v_cvt_pk_bf16_f32 v7, v128, v129
	s_waitcnt lgkmcnt(10)
	v_mfma_f32_32x32x16_bf16 v[50:65], v[186:189], v[178:181], v[50:65]
	ds_read_b64_tr_b16 v[194:195], v246 offset:51200
	ds_read_b64_tr_b16 v[196:197], v246 offset:51712
	ds_read_b128 v[228:231], v240 offset:6144
	v_add_f32_e32 v198, v124, v198
	v_add_f32_e32 v198, v125, v198
	v_add_f32_e32 v198, v126, v198
	v_add_f32_e32 v198, v127, v198
	s_waitcnt lgkmcnt(10)
; __device__ __forceinline__ int crow(int r,int hi){return (r&3)+8*(r>>2)+4*hi;}
; __device__ __forceinline__ float max3f(float a,float b,float c){float r;asm("v_max3_f32 %0, %1, %2, %3":"=v"(r):"v"(a),"v"(b),"v"(c));return r;}
; __device__ __forceinline__ float max2f(float a,float b){float r;asm("v_max_f32_e32 %0, %1, %2":"=v"(r):"v"(a),"v"(b));return r;}
;   #define PVG(i,PW,VF,NEXTI,X0,X1,Y0,Y1,EXTRA) do{ S.o[(i)&3]=MF32(__builtin_bit_cast(bf16x8,PW),VF,S.o[(i)&3]); if((NEXTI)<16){ VF=vfrag(vp,(NEXTI)<16?(NEXTI):0); } sa+=X0; sa+=X1; sa+=Y0; sa+=Y1; EXTRA; SB(); }while(0)
; template<int THRL,bool FIRST> __device__ __forceinline__ void decide(float rm,St&S,float*wsf,int r32,int hi){
;   if(FIRST){ S.mhat=rm; }
;   else if(__any(rm-S.mhat>(float)THRL)){
;     const float dl=__builtin_fmaxf(rm-S.mhat,0.f); S.mhat+=dl;
;     const float f=__builtin_amdgcn_exp2f(-dl); S.l_reg*=f; if(hi==0)wsf[r32]=f;
;     asm volatile("s_waitcnt lgkmcnt(0)":::"memory");
;     #pragma unroll
;     for(int r=0;r<16;++r){ const float fr=wsf[crow(r,hi)];
;       #pragma unroll
;       for(int d=0;d<4;++d)S.o[d][r]*=fr; }
;   }
; template<int THRL,bool FIRST> __device__ __forceinline__ void step_main(f32x16&p0,f32x16&p1,f32x16&n0,f32x16&n1,St&S,lds_cptr kpn,lds_cptr qp,lds_cptr vp,float*wsf,int r32,int hi,float&rm){
;     ...
;   float ma,mb;
;     ...
;   PVG(8,pw2,vfa,12,0.f,0.f,0.f,0.f, do{ma=max3f(n0[0],n0[1],n1[0]);mb=max3f(n0[2],n0[3],n1[1]);PINAB();}while(0));
;   PVG(9,pw2,vfb,13,0.f,0.f,0.f,0.f, do{ma=max3f(ma,n1[2],n1[3]);mb=max3f(mb,n0[4],n0[5]);PINAB();}while(0));
;   PVG(10,pw2,vfc,14,0.f,0.f,0.f,0.f, do{ma=max3f(ma,n0[6],n0[7]);mb=max3f(mb,n1[4],n1[5]);PINAB();}while(0));
;   PVG(11,pw2,vfd,15,0.f,0.f,0.f,0.f, do{ma=max3f(ma,n1[6],n1[7]);mb=max3f(mb,n0[8],n0[9]);PINAB();}while(0));
;   PVG(12,pw3,vfa,16,0.f,0.f,0.f,0.f, do{ma=max3f(ma,n0[10],n0[11]);mb=max3f(mb,n1[8],n1[9]);PINAB();}while(0));
;   PVG(13,pw3,vfb,16,0.f,0.f,0.f,0.f, do{ma=max3f(ma,n1[10],n1[11]);mb=max3f(mb,n0[12],n0[13]);PINAB();}while(0));
;   PVG(14,pw3,vfc,16,0.f,0.f,0.f,0.f, do{ma=max3f(ma,n0[14],n0[15]);mb=max3f(mb,n1[12],n1[13]);PINAB();}while(0));
;   PVG(15,pw3,vfd,16,0.f,0.f,0.f,0.f, do{ma=max3f(ma,n1[14],n1[15]);ma=max2f(ma,mb);PINAB();}while(0));
;     ...
;   { auto rr=__builtin_amdgcn_permlane32_swap(__float_as_uint(ma),__float_as_uint(ma),false,false); rm=max2f(__uint_as_float(rr[0]),__uint_as_float(rr[1])); }
	v_mfma_f32_32x32x16_bf16 v[66:81], v[186:189], v[182:185], v[66:81]
	ds_read_b64_tr_b16 v[178:179], v246 offset:55296
	ds_read_b64_tr_b16 v[180:181], v246 offset:55808
	ds_read_b128 v[232:235], v240 offset:6656
	v_add_f32_e32 v198, v128, v198
	v_add_f32_e32 v198, v129, v198
	v_add_f32_e32 v198, 0, v198
	s_waitcnt lgkmcnt(10)
	v_mfma_f32_32x32x16_bf16 v[18:33], v[12:15], v[8:11], v[18:33]
	ds_read_b64_tr_b16 v[182:183], v246 offset:44032
	ds_read_b64_tr_b16 v[184:185], v246 offset:44544
	v_max3_f32 v186, v98, v99, v82
	v_max3_f32 v187, v100, v101, v83
	s_nop 0
	s_waitcnt lgkmcnt(9)
	v_mfma_f32_32x32x16_bf16 v[34:49], v[12:15], v[190:193], v[34:49]
	ds_read_b64_tr_b16 v[8:9], v246 offset:48128
	ds_read_b64_tr_b16 v[10:11], v246 offset:48640
	v_max3_f32 v199, v186, v84, v85
	v_max3_f32 v200, v187, v102, v103
	s_nop 0
	s_waitcnt lgkmcnt(8)
	v_mfma_f32_32x32x16_bf16 v[50:65], v[12:15], v[194:197], v[50:65]
	ds_read_b64_tr_b16 v[186:187], v246 offset:52224
	ds_read_b64_tr_b16 v[188:189], v246 offset:52736
	v_max3_f32 v199, v199, v104, v105
	v_max3_f32 v200, v200, v86, v87
	s_nop 0
	s_waitcnt lgkmcnt(7)
	v_mfma_f32_32x32x16_bf16 v[66:81], v[12:15], v[178:181], v[66:81]
	ds_read_b64_tr_b16 v[190:191], v246 offset:56320
	ds_read_b64_tr_b16 v[192:193], v246 offset:56832
	v_max3_f32 v194, v199, v88, v89
	v_max3_f32 v195, v200, v106, v107
	s_nop 0
	s_waitcnt lgkmcnt(6)
	v_mfma_f32_32x32x16_bf16 v[18:33], v[4:7], v[182:185], v[18:33]
	v_max3_f32 v12, v194, v108, v109
	v_max3_f32 v13, v195, v90, v91
	s_nop 0
	s_waitcnt lgkmcnt(4)
	v_mfma_f32_32x32x16_bf16 v[34:49], v[4:7], v[8:11], v[34:49]
	v_max3_f32 v12, v12, v92, v93
	v_max3_f32 v13, v13, v110, v111
	s_nop 0
	s_waitcnt lgkmcnt(2)
	v_mfma_f32_32x32x16_bf16 v[50:65], v[4:7], v[186:189], v[50:65]
	v_max3_f32 v8, v12, v112, v113
	v_max3_f32 v9, v13, v94, v95
	s_nop 0
	s_waitcnt lgkmcnt(0)
	v_mfma_f32_32x32x16_bf16 v[66:81], v[4:7], v[190:193], v[66:81]
	v_max3_f32 v8, v8, v96, v97
	s_nop 0
	v_max_f32_e32 v8, v8, v9
	s_nop 0
	s_add_u32 s58, s58, 0x180000
	s_addc_u32 s59, s59, 0
	s_add_u32 s50, s50, 0x180000
	s_waitcnt vmcnt(0) lgkmcnt(0)
	s_barrier
	s_addc_u32 s51, s51, 0
	v_mov_b32_e32 v4, v8
	v_add_f32_e32 v251, v17, v198
	s_cmp_lt_u32 s90, s89
	v_permlane32_swap_b32_e32 v8, v4
	v_max_f32_e32 v178, v8, v4
	s_cbranch_scc0 .LBB0_285
.LBB0_278:
	v_mov_b32_e32 v126, v178
	v_cmp_lt_f32_e32 vcc, s69, v126
	s_cbranch_vccz .LBB0_282
	v_max_f32_e32 v126, v126, v126
	v_max_f32_e32 v126, 0, v126
	v_exp_f32_e64 v127, -v126
	s_and_saveexec_b64 s[60:61], s[6:7]
	ds_write_b32 v16, v127
	s_or_b64 exec, exec, s[60:61]
	s_waitcnt lgkmcnt(0)
	v_add_u32_e32 v140, s78, v2
	ds_read_b128 v[128:131], v140 offset:64
	ds_read_b128 v[132:135], v140 offset:96
	ds_read_b128 v[136:139], v140
	ds_read_b128 v[140:143], v140 offset:32
	v_add_f32_e32 v247, v247, v126
	v_sub_f32_e32 v146, v146, v126
	v_sub_f32_e32 v147, v147, v126
	v_sub_f32_e32 v148, v148, v126
	v_sub_f32_e32 v149, v149, v126
	v_sub_f32_e32 v150, v150, v126
	v_sub_f32_e32 v151, v151, v126
	v_sub_f32_e32 v152, v152, v126
	v_sub_f32_e32 v153, v153, v126
	v_sub_f32_e32 v154, v154, v126
	v_sub_f32_e32 v155, v155, v126
	v_sub_f32_e32 v156, v156, v126
	v_sub_f32_e32 v157, v157, v126
	v_sub_f32_e32 v158, v158, v126
	v_sub_f32_e32 v159, v159, v126
	v_sub_f32_e32 v160, v160, v126
	v_sub_f32_e32 v161, v161, v126
	v_sub_f32_e32 v82, v82, v126
	v_sub_f32_e32 v83, v83, v126
	v_sub_f32_e32 v84, v84, v126
	v_sub_f32_e32 v85, v85, v126
	v_sub_f32_e32 v86, v86, v126
	v_sub_f32_e32 v87, v87, v126
	v_sub_f32_e32 v88, v88, v126
	v_sub_f32_e32 v89, v89, v126
	v_sub_f32_e32 v90, v90, v126
	v_sub_f32_e32 v91, v91, v126
	v_sub_f32_e32 v92, v92, v126
	v_sub_f32_e32 v93, v93, v126
	v_sub_f32_e32 v94, v94, v126
	v_sub_f32_e32 v95, v95, v126
	v_sub_f32_e32 v96, v96, v126
	v_sub_f32_e32 v97, v97, v126
	v_sub_f32_e32 v98, v98, v126
	v_sub_f32_e32 v99, v99, v126
	v_sub_f32_e32 v100, v100, v126
	v_sub_f32_e32 v101, v101, v126
	v_sub_f32_e32 v102, v102, v126
	v_sub_f32_e32 v103, v103, v126
	v_sub_f32_e32 v104, v104, v126
	v_sub_f32_e32 v105, v105, v126
	v_sub_f32_e32 v106, v106, v126
	v_sub_f32_e32 v107, v107, v126
	v_sub_f32_e32 v108, v108, v126
	v_sub_f32_e32 v109, v109, v126
	v_sub_f32_e32 v110, v110, v126
	v_sub_f32_e32 v111, v111, v126
	v_sub_f32_e32 v112, v112, v126
	v_sub_f32_e32 v113, v113, v126
	v_mul_f32_e32 v251, v251, v127
	s_waitcnt lgkmcnt(2)
	v_pk_mul_f32 v[30:31], v[30:31], v[132:133]
	v_pk_mul_f32 v[26:27], v[26:27], v[128:129]
	s_waitcnt lgkmcnt(0)
	v_pk_mul_f32 v[22:23], v[22:23], v[140:141]
	v_pk_mul_f32 v[32:33], v[32:33], v[134:135]
	v_pk_mul_f32 v[28:29], v[28:29], v[130:131]
	v_pk_mul_f32 v[24:25], v[24:25], v[142:143]
	v_pk_mul_f32 v[20:21], v[20:21], v[138:139]
	v_pk_mul_f32 v[18:19], v[18:19], v[136:137]
	v_pk_mul_f32 v[46:47], v[46:47], v[132:133]
	v_pk_mul_f32 v[42:43], v[42:43], v[128:129]
	v_pk_mul_f32 v[38:39], v[38:39], v[140:141]
	v_pk_mul_f32 v[48:49], v[48:49], v[134:135]
	v_pk_mul_f32 v[44:45], v[44:45], v[130:131]
	v_pk_mul_f32 v[40:41], v[40:41], v[142:143]
	v_pk_mul_f32 v[36:37], v[36:37], v[138:139]
	v_pk_mul_f32 v[34:35], v[34:35], v[136:137]
	v_pk_mul_f32 v[62:63], v[62:63], v[132:133]
	v_pk_mul_f32 v[58:59], v[58:59], v[128:129]
	v_pk_mul_f32 v[54:55], v[54:55], v[140:141]
	v_pk_mul_f32 v[64:65], v[64:65], v[134:135]
	v_pk_mul_f32 v[60:61], v[60:61], v[130:131]
	v_pk_mul_f32 v[56:57], v[56:57], v[142:143]
	v_pk_mul_f32 v[52:53], v[52:53], v[138:139]
	v_pk_mul_f32 v[50:51], v[50:51], v[136:137]
	v_pk_mul_f32 v[78:79], v[78:79], v[132:133]
	v_pk_mul_f32 v[74:75], v[74:75], v[128:129]
	v_pk_mul_f32 v[70:71], v[70:71], v[140:141]
	v_pk_mul_f32 v[80:81], v[80:81], v[134:135]
	v_pk_mul_f32 v[76:77], v[76:77], v[130:131]
	v_pk_mul_f32 v[72:73], v[72:73], v[142:143]
	v_pk_mul_f32 v[68:69], v[68:69], v[138:139]
	v_pk_mul_f32 v[66:67], v[66:67], v[136:137]
; #define SB() __builtin_amdgcn_sched_barrier(0)
; #define MF32(a,b,c) __builtin_amdgcn_mfma_f32_32x32x16_bf16(a,b,c,0,0,0)
; #define EXP1(x) x=__builtin_amdgcn_exp2f((x)-mh_)
; __device__ __forceinline__ bf16x8 vfrag(lds_cptr vp,int i){ const s16x4 lo=vtr(vp+(i&3)*4096+(i>>2)*1024), hh=vtr(vp+(i&3)*4096+(i>>2)*1024+512); return (bf16x8){lo[0],lo[1],lo[2],lo[3],hh[0],hh[1],hh[2],hh[3]}; }
; __device__ __forceinline__ u32x4 packw(const f32x16&p,int base){ u32x4 w; w[0]=cvtpk_s(p[base],p[base+1]); w[1]=cvtpk_s(p[base+2],p[base+3]); w[2]=cvtpk_s(p[base+4],p[base+5]); w[3]=cvtpk_s(p[base+6],p[base+7]); return w; }
; template<int THRL,bool FIRST> __device__ __forceinline__ void step_main(f32x16&p0,f32x16&p1,f32x16&n0,f32x16&n1,St&S,lds_cptr kpn,lds_cptr qp,lds_cptr vp,float*wsf,int r32,int hi,float&rm){
;     ...
;   bf16x8 ka=KF(0),kb=KF(1),kc=KF(2),kd=KF(3),qa=QF(0),qb=QF(1);
;   decide<THRL,FIRST>(rm,S,wsf,r32,hi);
;   u32x4 pw0,pw1,pw2,pw3; const float mh_=S.mhat; const f32x16 z=f32x16{};
;   SB();
;   n0=MF32(ka,qa,z); ka=KF(4); EXP1(p0[0]);EXP1(p0[1]);EXP1(p0[2]); SB();
;   n1=MF32(kb,qa,z); kb=KF(5); qa=QF(2); EXP1(p0[3]);EXP1(p0[4]);EXP1(p0[5]); SB();
;   n0=MF32(kc,qb,n0);   kc=KF(6); EXP1(p0[6]);EXP1(p0[7]);EXP1(p0[8]); SB();
;   n1=MF32(kd,qb,n1);   kd=KF(7); qb=QF(3); EXP1(p0[9]);EXP1(p0[10]);EXP1(p0[11]); SB();
;   bf16x8 vfa=vfrag(vp,0);
;   n0=MF32(ka,qa,n0);   EXP1(p0[12]);EXP1(p0[13]);EXP1(p0[14]); pw0=packw(p0,0); SB();
;   bf16x8 vfb=vfrag(vp,1);
;   n1=MF32(kb,qa,n1);   EXP1(p0[15]);EXP1(p1[0]);EXP1(p1[1]); SB();
;   bf16x8 vfc=vfrag(vp,2);
;   n0=MF32(kc,qb,n0);   EXP1(p1[2]);EXP1(p1[3]);EXP1(p1[4]); pw1=packw(p0,8); SB();
;   bf16x8 vfd=vfrag(vp,3);
;   n1=MF32(kd,qb,n1);   EXP1(p1[5]);EXP1(p1[6]);EXP1(p1[7]); SB();
;     ...
;   float sa=p0[0]+p0[1];
;     ...
;   PVG(0,pw0,vfa,4, p0[2],p0[3],p0[4],p0[5],   do{EXP1(p1[8]);EXP1(p1[9]);}while(0));
;   PVG(1,pw0,vfb,5, p0[6],p0[7],p0[8],p0[9], do{EXP1(p1[10]);EXP1(p1[11]);}while(0));
;   PVG(2,pw0,vfc,6, p0[10],p0[11],p0[12],p0[13], do{EXP1(p1[12]);EXP1(p1[13]);}while(0));
;   PVG(3,pw0,vfd,7, p0[14],p0[15],p1[0],p1[1],   do{EXP1(p1[14]);EXP1(p1[15]);}while(0));
;   PVG(4,pw1,vfa,8, p1[2],p1[3],p1[4],p1[5],   pw2=packw(p1,0));
;   PVG(5,pw1,vfb,9, p1[6],p1[7],p1[8],p1[9], pw3=packw(p1,8));
;   PVG(6,pw1,vfc,10, p1[10],p1[11],p1[12],p1[13], do{}while(0));
;   PVG(7,pw1,vfd,11, p1[14],p1[15],0.f,0.f, do{}while(0));
.LBB0_282:
	s_add_i32 s4, s88, 0x2000
	s_cmpk_lg_i32 s88, 0x4000
	s_cselect_b32 s91, s4, 0
	v_mfma_f32_32x32x16_bf16 v[130:145], v[204:207], v[164:167], v[146:161]
	s_add_i32 s4, s91, s84
	s_mov_b32 s5, m0
	s_mov_b32 m0, s4
	s_nop 0
	global_load_lds_dwordx4 v252, s[58:59]
	s_mov_b32 m0, s5
	v_exp_f32_e32 v190, v98
	v_exp_f32_e32 v191, v99
	v_exp_f32_e32 v192, v100
	v_mfma_f32_32x32x16_bf16 v[114:129], v[208:211], v[164:167], v[146:161]
	s_mov_b32 s4, m0
	s_mov_b32 m0, s79
	s_nop 0
	global_load_lds_dwordx4 v250, s[50:51]
	s_mov_b32 m0, s4
	v_exp_f32_e32 v193, v101
	v_exp_f32_e32 v194, v102
	v_exp_f32_e32 v195, v103
	v_mfma_f32_32x32x16_bf16 v[130:145], v[212:215], v[168:171], v[130:145]
	s_add_u32 s60, s50, 0x80
	s_addc_u32 s61, s51, 0
	s_mov_b32 s4, m0
	s_mov_b32 m0, s41
	s_nop 0
	global_load_lds_dwordx4 v250, s[60:61]
	s_mov_b32 m0, s4
	v_exp_f32_e32 v196, v104
	v_exp_f32_e32 v197, v105
	v_exp_f32_e32 v198, v106
	v_mfma_f32_32x32x16_bf16 v[114:129], v[216:219], v[168:171], v[114:129]
	v_exp_f32_e32 v17, v107
	v_exp_f32_e32 v199, v108
	v_exp_f32_e32 v200, v109
	v_mfma_f32_32x32x16_bf16 v[130:145], v[220:223], v[172:175], v[130:145]
	v_exp_f32_e32 v201, v110
	ds_read_b64_tr_b16 v[4:5], v246 offset:24576
	ds_read_b64_tr_b16 v[6:7], v246 offset:25088
	v_exp_f32_e32 v202, v111
	v_exp_f32_e32 v178, v112
	v_cvt_pk_bf16_f32 v8, v190, v191
	v_cvt_pk_bf16_f32 v9, v192, v193
	v_cvt_pk_bf16_f32 v10, v194, v195
	v_cvt_pk_bf16_f32 v11, v196, v197
	v_mfma_f32_32x32x16_bf16 v[114:129], v[224:227], v[172:175], v[114:129]
	ds_read_b64_tr_b16 v[106:107], v246 offset:28672
	ds_read_b64_tr_b16 v[108:109], v246 offset:29184
	v_exp_f32_e32 v180, v82
	v_exp_f32_e32 v179, v113
	v_exp_f32_e32 v181, v83
	v_mfma_f32_32x32x16_bf16 v[130:145], v[228:231], v[236:239], v[130:145]
	ds_read_b64_tr_b16 v[110:111], v246 offset:32768
	ds_read_b64_tr_b16 v[112:113], v246 offset:33280
	v_exp_f32_e32 v182, v84
	v_exp_f32_e32 v183, v85
	v_exp_f32_e32 v184, v86
	v_cvt_pk_bf16_f32 v82, v198, v17
	v_cvt_pk_bf16_f32 v83, v199, v200
	v_cvt_pk_bf16_f32 v84, v201, v202
	v_cvt_pk_bf16_f32 v85, v178, v179
	v_mfma_f32_32x32x16_bf16 v[114:129], v[232:235], v[236:239], v[114:129]
	v_add_u32_e32 v240, s88, v249
	ds_read_b64_tr_b16 v[98:99], v246 offset:36864
	ds_read_b64_tr_b16 v[100:101], v246 offset:37376
	v_exp_f32_e32 v185, v87
	v_exp_f32_e32 v186, v88
	v_exp_f32_e32 v187, v89
	s_waitcnt lgkmcnt(6)
	v_mfma_f32_32x32x16_bf16 v[18:33], v[8:11], v[4:7], v[18:33]
	ds_read_b128 v[204:207], v240
	v_add_f32_e32 v86, v190, v191
	ds_read_b64_tr_b16 v[12:13], v246 offset:25600
	ds_read_b64_tr_b16 v[14:15], v246 offset:26112
	v_add_f32_e32 v86, v192, v86
	v_exp_f32_e32 v103, v91
	v_add_f32_e32 v4, v193, v86
	v_add_f32_e32 v4, v194, v4
	v_add_f32_e32 v86, v195, v4
	v_exp_f32_e32 v102, v90
	s_waitcnt lgkmcnt(7)
	v_mfma_f32_32x32x16_bf16 v[34:49], v[8:11], v[106:109], v[34:49]
	ds_read_b64_tr_b16 v[4:5], v246 offset:29696
	ds_read_b64_tr_b16 v[6:7], v246 offset:30208
	ds_read_b128 v[208:211], v240 offset:512
	v_add_f32_e32 v86, v196, v86
	v_add_f32_e32 v86, v197, v86
	v_add_f32_e32 v86, v198, v86
	v_exp_f32_e32 v104, v92
	v_add_f32_e32 v17, v17, v86
	v_exp_f32_e32 v105, v93
	s_waitcnt lgkmcnt(8)
	v_mfma_f32_32x32x16_bf16 v[50:65], v[8:11], v[110:113], v[50:65]
	ds_read_b64_tr_b16 v[86:87], v246 offset:33792
	ds_read_b64_tr_b16 v[88:89], v246 offset:34304
	ds_read_b128 v[212:215], v240 offset:2048
	v_add_f32_e32 v17, v199, v17
	v_add_f32_e32 v17, v200, v17
	v_add_f32_e32 v17, v201, v17
	v_exp_f32_e32 v106, v94
	v_add_f32_e32 v17, v202, v17
	v_exp_f32_e32 v107, v95
	s_waitcnt lgkmcnt(9)
	v_mfma_f32_32x32x16_bf16 v[66:81], v[8:11], v[98:101], v[66:81]
	ds_read_b64_tr_b16 v[90:91], v246 offset:37888
	ds_read_b64_tr_b16 v[92:93], v246 offset:38400
	ds_read_b128 v[216:219], v240 offset:2560
	v_add_f32_e32 v17, v178, v17
	v_add_f32_e32 v8, v179, v17
	v_add_f32_e32 v8, v180, v8
	v_exp_f32_e32 v108, v96
	v_add_f32_e32 v17, v181, v8
	v_exp_f32_e32 v109, v97
	s_waitcnt lgkmcnt(9)
; __device__ __forceinline__ int crow(int r,int hi){return (r&3)+8*(r>>2)+4*hi;}
; __device__ __forceinline__ float max3f(float a,float b,float c){float r;asm("v_max3_f32 %0, %1, %2, %3":"=v"(r):"v"(a),"v"(b),"v"(c));return r;}
; __device__ __forceinline__ float max2f(float a,float b){float r;asm("v_max_f32_e32 %0, %1, %2":"=v"(r):"v"(a),"v"(b));return r;}
;   #define PVG(i,PW,VF,NEXTI,X0,X1,Y0,Y1,EXTRA) do{ S.o[(i)&3]=MF32(__builtin_bit_cast(bf16x8,PW),VF,S.o[(i)&3]); if((NEXTI)<16){ VF=vfrag(vp,(NEXTI)<16?(NEXTI):0); } sa+=X0; sa+=X1; sa+=Y0; sa+=Y1; EXTRA; SB(); }while(0)
; template<int THRL,bool FIRST> __device__ __forceinline__ void decide(float rm,St&S,float*wsf,int r32,int hi){
;   if(FIRST){ S.mhat=rm; }
;   else if(__any(rm-S.mhat>(float)THRL)){
;     const float dl=__builtin_fmaxf(rm-S.mhat,0.f); S.mhat+=dl;
;     const float f=__builtin_amdgcn_exp2f(-dl); S.l_reg*=f; if(hi==0)wsf[r32]=f;
;     asm volatile("s_waitcnt lgkmcnt(0)":::"memory");
;     #pragma unroll
;     for(int r=0;r<16;++r){ const float fr=wsf[crow(r,hi)];
;       #pragma unroll
;       for(int d=0;d<4;++d)S.o[d][r]*=fr; }
;   }
; template<int THRL,bool FIRST> __device__ __forceinline__ void step_main(f32x16&p0,f32x16&p1,f32x16&n0,f32x16&n1,St&S,lds_cptr kpn,lds_cptr qp,lds_cptr vp,float*wsf,int r32,int hi,float&rm){
;     ...
;   float ma,mb;
;     ...
;   PVG(8,pw2,vfa,12,0.f,0.f,0.f,0.f, do{ma=max3f(n0[0],n0[1],n1[0]);mb=max3f(n0[2],n0[3],n1[1]);PINAB();}while(0));
;   PVG(9,pw2,vfb,13,0.f,0.f,0.f,0.f, do{ma=max3f(ma,n1[2],n1[3]);mb=max3f(mb,n0[4],n0[5]);PINAB();}while(0));
;   PVG(10,pw2,vfc,14,0.f,0.f,0.f,0.f, do{ma=max3f(ma,n0[6],n0[7]);mb=max3f(mb,n1[4],n1[5]);PINAB();}while(0));
;   PVG(11,pw2,vfd,15,0.f,0.f,0.f,0.f, do{ma=max3f(ma,n1[6],n1[7]);mb=max3f(mb,n0[8],n0[9]);PINAB();}while(0));
;   PVG(12,pw3,vfa,16,0.f,0.f,0.f,0.f, do{ma=max3f(ma,n0[10],n0[11]);mb=max3f(mb,n1[8],n1[9]);PINAB();}while(0));
;   PVG(13,pw3,vfb,16,0.f,0.f,0.f,0.f, do{ma=max3f(ma,n1[10],n1[11]);mb=max3f(mb,n0[12],n0[13]);PINAB();}while(0));
;   PVG(14,pw3,vfc,16,0.f,0.f,0.f,0.f, do{ma=max3f(ma,n0[14],n0[15]);mb=max3f(mb,n1[12],n1[13]);PINAB();}while(0));
;   PVG(15,pw3,vfd,16,0.f,0.f,0.f,0.f, do{ma=max3f(ma,n1[14],n1[15]);ma=max2f(ma,mb);PINAB();}while(0));
;     ...
;   { auto rr=__builtin_amdgcn_permlane32_swap(__float_as_uint(ma),__float_as_uint(ma),false,false); rm=max2f(__uint_as_float(rr[0]),__uint_as_float(rr[1])); }
	v_mfma_f32_32x32x16_bf16 v[18:33], v[82:85], v[12:15], v[18:33]
	ds_read_b64_tr_b16 v[8:9], v246 offset:26624
	ds_read_b64_tr_b16 v[10:11], v246 offset:27136
	ds_read_b128 v[220:223], v240 offset:4096
	v_add_f32_e32 v17, v182, v17
	v_add_f32_e32 v17, v183, v17
	v_add_f32_e32 v17, v184, v17
	v_add_f32_e32 v17, v185, v17
	v_cvt_pk_bf16_f32 v12, v180, v181
	v_cvt_pk_bf16_f32 v13, v182, v183
	v_cvt_pk_bf16_f32 v14, v184, v185
	v_cvt_pk_bf16_f32 v15, v186, v187
	s_waitcnt lgkmcnt(10)
	v_mfma_f32_32x32x16_bf16 v[34:49], v[82:85], v[4:7], v[34:49]
	ds_read_b64_tr_b16 v[94:95], v246 offset:30720
	ds_read_b64_tr_b16 v[96:97], v246 offset:31232
	ds_read_b128 v[224:227], v240 offset:4608
	v_add_f32_e32 v17, v186, v17
	v_add_f32_e32 v17, v187, v17
	v_add_f32_e32 v17, v102, v17
	v_add_f32_e32 v17, v103, v17
	v_cvt_pk_bf16_f32 v4, v102, v103
	v_cvt_pk_bf16_f32 v5, v104, v105
	v_cvt_pk_bf16_f32 v6, v106, v107
	v_cvt_pk_bf16_f32 v7, v108, v109
	s_waitcnt lgkmcnt(10)
	v_mfma_f32_32x32x16_bf16 v[50:65], v[82:85], v[86:89], v[50:65]
	ds_read_b64_tr_b16 v[98:99], v246 offset:34816
	ds_read_b64_tr_b16 v[100:101], v246 offset:35328
	ds_read_b128 v[228:231], v240 offset:6144
	v_add_f32_e32 v17, v104, v17
	v_add_f32_e32 v17, v105, v17
	v_add_f32_e32 v17, v106, v17
	v_add_f32_e32 v17, v107, v17
	s_waitcnt lgkmcnt(10)
	v_mfma_f32_32x32x16_bf16 v[66:81], v[82:85], v[90:93], v[66:81]
	ds_read_b64_tr_b16 v[86:87], v246 offset:38912
	ds_read_b64_tr_b16 v[88:89], v246 offset:39424
	ds_read_b128 v[232:235], v240 offset:6656
	v_add_f32_e32 v17, v108, v17
	v_add_f32_e32 v17, v109, v17
	v_add_f32_e32 v17, 0, v17
	s_waitcnt lgkmcnt(10)
	v_mfma_f32_32x32x16_bf16 v[18:33], v[12:15], v[8:11], v[18:33]
	ds_read_b64_tr_b16 v[82:83], v246 offset:27648
	ds_read_b64_tr_b16 v[84:85], v246 offset:28160
	v_max3_f32 v90, v130, v131, v114
	v_max3_f32 v91, v132, v133, v115
	s_nop 0
	s_waitcnt lgkmcnt(9)
	v_mfma_f32_32x32x16_bf16 v[34:49], v[12:15], v[94:97], v[34:49]
	ds_read_b64_tr_b16 v[8:9], v246 offset:31744
	ds_read_b64_tr_b16 v[10:11], v246 offset:32256
	v_max3_f32 v102, v90, v116, v117
	v_max3_f32 v103, v91, v134, v135
	s_nop 0
	s_waitcnt lgkmcnt(8)
	v_mfma_f32_32x32x16_bf16 v[50:65], v[12:15], v[98:101], v[50:65]
	ds_read_b64_tr_b16 v[90:91], v246 offset:35840
	ds_read_b64_tr_b16 v[92:93], v246 offset:36352
	v_max3_f32 v102, v102, v136, v137
	v_max3_f32 v103, v103, v118, v119
	s_nop 0
	s_waitcnt lgkmcnt(7)
	v_mfma_f32_32x32x16_bf16 v[66:81], v[12:15], v[86:89], v[66:81]
	ds_read_b64_tr_b16 v[94:95], v246 offset:39936
	ds_read_b64_tr_b16 v[96:97], v246 offset:40448
	v_max3_f32 v98, v102, v120, v121
	v_max3_f32 v99, v103, v138, v139
	s_nop 0
	s_waitcnt lgkmcnt(6)
	v_mfma_f32_32x32x16_bf16 v[18:33], v[4:7], v[82:85], v[18:33]
	v_max3_f32 v12, v98, v140, v141
	v_max3_f32 v13, v99, v122, v123
	s_nop 0
	s_waitcnt lgkmcnt(4)
	v_mfma_f32_32x32x16_bf16 v[34:49], v[4:7], v[8:11], v[34:49]
	v_max3_f32 v12, v12, v124, v125
	v_max3_f32 v13, v13, v142, v143
	s_nop 0
	s_waitcnt lgkmcnt(2)
	v_mfma_f32_32x32x16_bf16 v[50:65], v[4:7], v[90:93], v[50:65]
	v_max3_f32 v8, v12, v144, v145
	v_max3_f32 v9, v13, v126, v127
	s_nop 0
	s_waitcnt lgkmcnt(0)
	v_mfma_f32_32x32x16_bf16 v[66:81], v[4:7], v[94:97], v[66:81]
	v_max3_f32 v8, v8, v128, v129
	s_nop 0
	v_max_f32_e32 v8, v8, v9
	s_nop 0
	v_mov_b32_e32 v162, v8
	v_mov_b32_e32 v163, v8
	s_waitcnt vmcnt(0) lgkmcnt(0)
	s_barrier
	v_permlane32_swap_b32_e32 v162, v163
	v_max_f32_e32 v94, v162, v163
	v_add_f32_e32 v17, v251, v17
	v_cmp_lt_f32_e32 vcc, s69, v94
	s_cbranch_vccz .LBB0_277
	v_max_f32_e32 v94, v94, v94
	v_max_f32_e32 v94, 0, v94
	v_exp_f32_e64 v95, -v94
	s_and_saveexec_b64 s[60:61], s[6:7]
	s_cbranch_execz .LBB0_276
	ds_write_b32 v16, v95
	s_branch .LBB0_276

; #define SB() __builtin_amdgcn_sched_barrier(0)
; #define MF32(a,b,c) __builtin_amdgcn_mfma_f32_32x32x16_bf16(a,b,c,0,0,0)
; #define EXP1(x) x=__builtin_amdgcn_exp2f((x)-mh_)
; __device__ __forceinline__ bf16x8 vfrag(lds_cptr vp,int i){ const s16x4 lo=vtr(vp+(i&3)*4096+(i>>2)*1024), hh=vtr(vp+(i&3)*4096+(i>>2)*1024+512); return (bf16x8){lo[0],lo[1],lo[2],lo[3],hh[0],hh[1],hh[2],hh[3]}; }
; __device__ __forceinline__ u32x4 packw(const f32x16&p,int base){ u32x4 w; w[0]=cvtpk_s(p[base],p[base+1]); w[1]=cvtpk_s(p[base+2],p[base+3]); w[2]=cvtpk_s(p[base+4],p[base+5]); w[3]=cvtpk_s(p[base+6],p[base+7]); return w; }
; template<int THRL,bool FIRST> __device__ __forceinline__ void step_main(f32x16&p0,f32x16&p1,f32x16&n0,f32x16&n1,St&S,lds_cptr kpn,lds_cptr qp,lds_cptr vp,float*wsf,int r32,int hi,float&rm){
;     ...
;   bf16x8 ka=KF(0),kb=KF(1),kc=KF(2),kd=KF(3),qa=QF(0),qb=QF(1);
;   decide<THRL,FIRST>(rm,S,wsf,r32,hi);
;   u32x4 pw0,pw1,pw2,pw3; const float mh_=S.mhat; const f32x16 z=f32x16{};
;   SB();
;   n0=MF32(ka,qa,z); ka=KF(4); EXP1(p0[0]);EXP1(p0[1]);EXP1(p0[2]); SB();
;   n1=MF32(kb,qa,z); kb=KF(5); qa=QF(2); EXP1(p0[3]);EXP1(p0[4]);EXP1(p0[5]); SB();
;   n0=MF32(kc,qb,n0);   kc=KF(6); EXP1(p0[6]);EXP1(p0[7]);EXP1(p0[8]); SB();
;   n1=MF32(kd,qb,n1);   kd=KF(7); qb=QF(3); EXP1(p0[9]);EXP1(p0[10]);EXP1(p0[11]); SB();
;   bf16x8 vfa=vfrag(vp,0);
;   n0=MF32(ka,qa,n0);   EXP1(p0[12]);EXP1(p0[13]);EXP1(p0[14]); pw0=packw(p0,0); SB();
;   bf16x8 vfb=vfrag(vp,1);
;   n1=MF32(kb,qa,n1);   EXP1(p0[15]);EXP1(p1[0]);EXP1(p1[1]); SB();
;   bf16x8 vfc=vfrag(vp,2);
;   n0=MF32(kc,qb,n0);   EXP1(p1[2]);EXP1(p1[3]);EXP1(p1[4]); pw1=packw(p0,8); SB();
;   bf16x8 vfd=vfrag(vp,3);
;   n1=MF32(kd,qb,n1);   EXP1(p1[5]);EXP1(p1[6]);EXP1(p1[7]); SB();
;     ...
;   float sa=p0[0]+p0[1];
;     ...
;   PVG(0,pw0,vfa,4, p0[2],p0[3],p0[4],p0[5],   do{EXP1(p1[8]);EXP1(p1[9]);}while(0));
;   PVG(1,pw0,vfb,5, p0[6],p0[7],p0[8],p0[9], do{EXP1(p1[10]);EXP1(p1[11]);}while(0));
;   PVG(2,pw0,vfc,6, p0[10],p0[11],p0[12],p0[13], do{EXP1(p1[12]);EXP1(p1[13]);}while(0));
;   PVG(3,pw0,vfd,7, p0[14],p0[15],p1[0],p1[1],   do{EXP1(p1[14]);EXP1(p1[15]);}while(0));
;   PVG(4,pw1,vfa,8, p1[2],p1[3],p1[4],p1[5],   pw2=packw(p1,0));
;   PVG(5,pw1,vfb,9, p1[6],p1[7],p1[8],p1[9], pw3=packw(p1,8));
;   PVG(6,pw1,vfc,10, p1[10],p1[11],p1[12],p1[13], do{}while(0));
;   PVG(7,pw1,vfd,11, p1[14],p1[15],0.f,0.f, do{}while(0));
.LBB0_433:
	s_waitcnt lgkmcnt(1)
	v_mfma_f32_32x32x16_bf16 v[98:113], v[218:221], v[214:217], 0
	ds_read_b128 v[178:181], v249 offset:20480
	v_sub_f32_e32 v82, v131, v247
	v_sub_f32_e32 v17, v130, v247
	v_exp_f32_e32 v190, v82
	v_sub_f32_e32 v82, v132, v247
	v_exp_f32_e32 v17, v17
	v_exp_f32_e32 v191, v82
	v_sub_f32_e32 v82, v133, v247
	v_exp_f32_e32 v192, v82
	v_sub_f32_e32 v82, v134, v247
	v_exp_f32_e32 v193, v82
	v_sub_f32_e32 v82, v135, v247
	v_exp_f32_e32 v194, v82
	v_mfma_f32_32x32x16_bf16 v[82:97], v[210:213], v[214:217], 0
	ds_read_b128 v[182:185], v249 offset:20992
	ds_read_b128 v[186:189], v248 offset:2048
	s_waitcnt lgkmcnt(3)
	v_mfma_f32_32x32x16_bf16 v[98:113], v[12:15], v[8:11], v[98:113]
	ds_read_b128 v[130:133], v249 offset:22528
	v_sub_f32_e32 v134, v136, v247
	v_exp_f32_e32 v195, v134
	v_sub_f32_e32 v134, v137, v247
	v_exp_f32_e32 v196, v134
	v_sub_f32_e32 v134, v138, v247
	v_exp_f32_e32 v197, v134
	v_mfma_f32_32x32x16_bf16 v[82:97], v[4:7], v[8:11], v[82:97]
	ds_read_b128 v[12:15], v249 offset:23040
	ds_read_b128 v[134:137], v248 offset:3072
	v_sub_f32_e32 v138, v139, v247
	v_exp_f32_e32 v198, v138
	v_sub_f32_e32 v138, v140, v247
	v_exp_f32_e32 v199, v138
	v_sub_f32_e32 v138, v141, v247
	v_exp_f32_e32 v200, v138
	s_waitcnt lgkmcnt(3)
	v_mfma_f32_32x32x16_bf16 v[98:113], v[178:181], v[186:189], v[98:113]
	ds_read_b64_tr_b16 v[4:5], v246 offset:40960
	ds_read_b64_tr_b16 v[6:7], v246 offset:41472
	v_sub_f32_e32 v8, v142, v247
	v_exp_f32_e32 v201, v8
	v_sub_f32_e32 v8, v143, v247
	v_exp_f32_e32 v202, v8
	v_sub_f32_e32 v8, v144, v247
	v_exp_f32_e32 v179, v8
	v_cvt_pk_bf16_f32 v8, v17, v190
	v_cvt_pk_bf16_f32 v9, v191, v192
	v_cvt_pk_bf16_f32 v10, v193, v194
	v_cvt_pk_bf16_f32 v11, v195, v196
	v_mfma_f32_32x32x16_bf16 v[82:97], v[182:185], v[186:189], v[82:97]
	ds_read_b64_tr_b16 v[138:139], v246 offset:45056
	ds_read_b64_tr_b16 v[140:141], v246 offset:45568
	v_sub_f32_e32 v114, v114, v247
	v_sub_f32_e32 v142, v145, v247
	v_exp_f32_e32 v181, v114
	v_sub_f32_e32 v114, v115, v247
	v_exp_f32_e32 v180, v142
	v_exp_f32_e32 v203, v114
	s_waitcnt lgkmcnt(4)
	v_mfma_f32_32x32x16_bf16 v[98:113], v[130:133], v[134:137], v[98:113]
	ds_read_b64_tr_b16 v[142:143], v246 offset:49152
	ds_read_b64_tr_b16 v[144:145], v246 offset:49664
	v_sub_f32_e32 v114, v116, v247
	v_exp_f32_e32 v182, v114
	v_sub_f32_e32 v114, v117, v247
	v_exp_f32_e32 v183, v114
	v_sub_f32_e32 v114, v118, v247
	v_exp_f32_e32 v184, v114
	v_cvt_pk_bf16_f32 v114, v197, v198
	v_cvt_pk_bf16_f32 v115, v199, v200
	v_cvt_pk_bf16_f32 v116, v201, v202
	v_cvt_pk_bf16_f32 v117, v179, v180
	v_mfma_f32_32x32x16_bf16 v[82:97], v[12:15], v[134:137], v[82:97]
	ds_read_b64_tr_b16 v[130:131], v246 offset:53248
	ds_read_b64_tr_b16 v[132:133], v246 offset:53760
	v_sub_f32_e32 v118, v119, v247
	v_exp_f32_e32 v185, v118
	v_sub_f32_e32 v118, v120, v247
	v_exp_f32_e32 v186, v118
	v_sub_f32_e32 v118, v121, v247
	v_exp_f32_e32 v187, v118
	s_waitcnt lgkmcnt(6)
	v_mfma_f32_32x32x16_bf16 v[18:33], v[8:11], v[4:7], v[18:33]
	ds_read_b64_tr_b16 v[12:13], v246 offset:41984
	ds_read_b64_tr_b16 v[14:15], v246 offset:42496
	v_sub_f32_e32 v118, v122, v247
	v_exp_f32_e32 v134, v118
	v_sub_f32_e32 v118, v123, v247
	v_exp_f32_e32 v135, v118
	s_waitcnt lgkmcnt(6)
	v_mfma_f32_32x32x16_bf16 v[34:49], v[8:11], v[138:141], v[34:49]
	ds_read_b64_tr_b16 v[4:5], v246 offset:46080
	ds_read_b64_tr_b16 v[6:7], v246 offset:46592
	v_sub_f32_e32 v118, v124, v247
	v_exp_f32_e32 v136, v118
	v_sub_f32_e32 v118, v125, v247
	v_exp_f32_e32 v137, v118
	s_waitcnt lgkmcnt(6)
	v_mfma_f32_32x32x16_bf16 v[50:65], v[8:11], v[142:145], v[50:65]
	ds_read_b64_tr_b16 v[118:119], v246 offset:50176
	ds_read_b64_tr_b16 v[120:121], v246 offset:50688
	v_sub_f32_e32 v122, v126, v247
	v_exp_f32_e32 v138, v122
	v_sub_f32_e32 v122, v127, v247
	v_exp_f32_e32 v139, v122
	s_waitcnt lgkmcnt(6)
	v_mfma_f32_32x32x16_bf16 v[66:81], v[8:11], v[130:133], v[66:81]
	ds_read_b64_tr_b16 v[122:123], v246 offset:54272
	ds_read_b64_tr_b16 v[124:125], v246 offset:54784
	v_sub_f32_e32 v126, v128, v247
	v_exp_f32_e32 v140, v126
	v_sub_f32_e32 v126, v129, v247
	v_exp_f32_e32 v141, v126
	s_waitcnt lgkmcnt(6)
	v_mfma_f32_32x32x16_bf16 v[18:33], v[114:117], v[12:15], v[18:33]
	ds_read_b64_tr_b16 v[8:9], v246 offset:43008
	ds_read_b64_tr_b16 v[10:11], v246 offset:43520
	v_cvt_pk_bf16_f32 v126, v181, v203
	v_cvt_pk_bf16_f32 v127, v182, v183
	v_cvt_pk_bf16_f32 v128, v184, v185
	v_cvt_pk_bf16_f32 v129, v186, v187
	s_waitcnt lgkmcnt(6)
	v_mfma_f32_32x32x16_bf16 v[34:49], v[114:117], v[4:7], v[34:49]
	ds_read_b64_tr_b16 v[12:13], v246 offset:47104
	ds_read_b64_tr_b16 v[14:15], v246 offset:47616
	v_cvt_pk_bf16_f32 v130, v134, v135
	v_cvt_pk_bf16_f32 v131, v136, v137
	v_cvt_pk_bf16_f32 v132, v138, v139
	v_cvt_pk_bf16_f32 v133, v140, v141
	s_waitcnt lgkmcnt(6)
	v_mfma_f32_32x32x16_bf16 v[50:65], v[114:117], v[118:121], v[50:65]
	ds_read_b64_tr_b16 v[4:5], v246 offset:51200
	ds_read_b64_tr_b16 v[6:7], v246 offset:51712
	s_waitcnt lgkmcnt(6)
	v_mfma_f32_32x32x16_bf16 v[66:81], v[114:117], v[122:125], v[66:81]
	ds_read_b64_tr_b16 v[118:119], v246 offset:55296
	ds_read_b64_tr_b16 v[120:121], v246 offset:55808
	s_waitcnt lgkmcnt(6)
; __device__ __forceinline__ float max3f(float a,float b,float c){float r;asm("v_max3_f32 %0, %1, %2, %3":"=v"(r):"v"(a),"v"(b),"v"(c));return r;}
; __device__ __forceinline__ float max2f(float a,float b){float r;asm("v_max_f32_e32 %0, %1, %2":"=v"(r):"v"(a),"v"(b));return r;}
; #define A128_WAITBAR() asm volatile("s_waitcnt vmcnt(0) lgkmcnt(0)\n\ts_barrier":::"memory")
;   #define PINAB() asm volatile("":"+v"(ma),"+v"(mb))
;   #define DMA_K(t,so) glds16s((const char*)K+(size_t)(t)*(64*PIN*2),koff,(unsigned)__builtin_amdgcn_readfirstlane(kdst+(so)))
; template<int THRL,bool FIRST> __device__ __forceinline__ void step_main(f32x16&p0,f32x16&p1,f32x16&n0,f32x16&n1,St&S,lds_cptr kpn,lds_cptr qp,lds_cptr vp,float*wsf,int r32,int hi,float&rm){
;     ...
;   float ma,mb;
;     ...
;   PVG(8,pw2,vfa,12,0.f,0.f,0.f,0.f, do{ma=max3f(n0[0],n0[1],n1[0]);mb=max3f(n0[2],n0[3],n1[1]);PINAB();}while(0));
;   PVG(9,pw2,vfb,13,0.f,0.f,0.f,0.f, do{ma=max3f(ma,n1[2],n1[3]);mb=max3f(mb,n0[4],n0[5]);PINAB();}while(0));
;   PVG(10,pw2,vfc,14,0.f,0.f,0.f,0.f, do{ma=max3f(ma,n0[6],n0[7]);mb=max3f(mb,n1[4],n1[5]);PINAB();}while(0));
;   PVG(11,pw2,vfd,15,0.f,0.f,0.f,0.f, do{ma=max3f(ma,n1[6],n1[7]);mb=max3f(mb,n0[8],n0[9]);PINAB();}while(0));
;   PVG(12,pw3,vfa,16,0.f,0.f,0.f,0.f, do{ma=max3f(ma,n0[10],n0[11]);mb=max3f(mb,n1[8],n1[9]);PINAB();}while(0));
;   PVG(13,pw3,vfb,16,0.f,0.f,0.f,0.f, do{ma=max3f(ma,n1[10],n1[11]);mb=max3f(mb,n0[12],n0[13]);PINAB();}while(0));
;   PVG(14,pw3,vfc,16,0.f,0.f,0.f,0.f, do{ma=max3f(ma,n0[14],n0[15]);mb=max3f(mb,n1[12],n1[13]);PINAB();}while(0));
;   PVG(15,pw3,vfd,16,0.f,0.f,0.f,0.f, do{ma=max3f(ma,n1[14],n1[15]);ma=max2f(ma,mb);PINAB();}while(0));
;     ...
;   { auto rr=__builtin_amdgcn_permlane32_swap(__float_as_uint(ma),__float_as_uint(ma),false,false); rm=max2f(__uint_as_float(rr[0]),__uint_as_float(rr[1])); }
;     ...
;   S.l_reg+=sa;
; template<int THRL> __device__ __forceinline__ void unit(int qb,const bf16*Q,const bf16*K,const bf16*V,bf16*O,char*shm){
;     ...
;     step_main<THRL,true>(pA0,pA1,pB0,pB1,S,kp0+ks1,qp,vp0,wsf,r32,hi,rm); A128_WAITBAR(); ROT();
;     DMA_K(3,ks2); DMA_V(2,0);
;     step_main<THRL,false>(pB0,pB1,pA0,pA1,S,kp0+ks1,qp,vp0+VBUF,wsf,r32,hi,rm); A128_WAITBAR(); ROT();
;     for(t=2;t<NT-4;t+=2){
;       DMA_K(t+2,ks2); DMA_V(t+1,VBUF);
;       step_main<THRL,false>(pA0,pA1,pB0,pB1,S,kp0+ks1,qp,vp0,wsf,r32,hi,rm); A128_WAITBAR(); ROT();
	v_mfma_f32_32x32x16_bf16 v[18:33], v[126:129], v[8:11], v[18:33]
	ds_read_b64_tr_b16 v[114:115], v246 offset:44032
	ds_read_b64_tr_b16 v[116:117], v246 offset:44544
	v_max3_f32 v122, v98, v99, v82
	v_max3_f32 v123, v100, v101, v83
	s_nop 0
	s_waitcnt lgkmcnt(6)
	v_mfma_f32_32x32x16_bf16 v[34:49], v[126:129], v[12:15], v[34:49]
	ds_read_b64_tr_b16 v[8:9], v246 offset:48128
	ds_read_b64_tr_b16 v[10:11], v246 offset:48640
	v_max3_f32 v122, v122, v84, v85
	v_max3_f32 v123, v123, v102, v103
	s_nop 0
	s_waitcnt lgkmcnt(6)
	v_mfma_f32_32x32x16_bf16 v[50:65], v[126:129], v[4:7], v[50:65]
	ds_read_b64_tr_b16 v[12:13], v246 offset:52224
	ds_read_b64_tr_b16 v[14:15], v246 offset:52736
	v_max3_f32 v122, v122, v104, v105
	v_max3_f32 v123, v123, v86, v87
	s_nop 0
	s_waitcnt lgkmcnt(6)
	v_mfma_f32_32x32x16_bf16 v[66:81], v[126:129], v[118:121], v[66:81]
	ds_read_b64_tr_b16 v[4:5], v246 offset:56320
	ds_read_b64_tr_b16 v[6:7], v246 offset:56832
	v_max3_f32 v122, v122, v88, v89
	v_max3_f32 v123, v123, v106, v107
	s_nop 0
	s_waitcnt lgkmcnt(6)
	v_mfma_f32_32x32x16_bf16 v[18:33], v[130:133], v[114:117], v[18:33]
	v_max3_f32 v118, v122, v108, v109
	v_max3_f32 v119, v123, v90, v91
	s_nop 0
	s_waitcnt lgkmcnt(4)
	v_mfma_f32_32x32x16_bf16 v[34:49], v[130:133], v[8:11], v[34:49]
	v_max3_f32 v114, v118, v92, v93
	v_max3_f32 v115, v119, v110, v111
	s_nop 0
	s_waitcnt lgkmcnt(2)
	v_mfma_f32_32x32x16_bf16 v[50:65], v[130:133], v[12:15], v[50:65]
	v_max3_f32 v8, v114, v112, v113
	v_max3_f32 v9, v115, v94, v95
	s_nop 0
	s_waitcnt lgkmcnt(0)
	v_mfma_f32_32x32x16_bf16 v[66:81], v[130:133], v[4:7], v[66:81]
	v_max3_f32 v8, v8, v96, v97
	s_nop 0
	v_max_f32_e32 v8, v8, v9
	s_nop 0
	s_nop 0
	v_mov_b32_e32 v4, v8
	s_nop 1
	v_permlane32_swap_b32_e32 v8, v4
	v_max_f32_e32 v178, v8, v4
	v_add_f32_e32 v4, v17, v190
	v_add_f32_e32 v4, v191, v4
	v_add_f32_e32 v4, v192, v4
	v_add_f32_e32 v4, v193, v4
	v_add_f32_e32 v4, v194, v4
	v_add_f32_e32 v4, v195, v4
	v_add_f32_e32 v4, v196, v4
	v_add_f32_e32 v4, v197, v4
	v_add_f32_e32 v4, v198, v4
	v_add_f32_e32 v4, v199, v4
	v_add_f32_e32 v4, v200, v4
	v_add_f32_e32 v4, v201, v4
	v_add_f32_e32 v4, v202, v4
	v_add_f32_e32 v4, v179, v4
	v_add_f32_e32 v4, v180, v4
	v_add_f32_e32 v4, v181, v4
	v_add_f32_e32 v4, v203, v4
	v_add_f32_e32 v4, v182, v4
	v_add_f32_e32 v4, v183, v4
	v_add_f32_e32 v4, v184, v4
	v_add_f32_e32 v4, v185, v4
	v_add_f32_e32 v4, v186, v4
	v_add_f32_e32 v4, v187, v4
	v_add_f32_e32 v4, v134, v4
	v_add_f32_e32 v4, v135, v4
	v_add_f32_e32 v4, v136, v4
	v_add_f32_e32 v4, v137, v4
	v_add_f32_e32 v4, v138, v4
	v_add_f32_e32 v4, v139, v4
	v_add_f32_e32 v4, v140, v4
	s_waitcnt vmcnt(0) lgkmcnt(0)
	s_barrier
	v_add_f32_e32 v4, v141, v4
	v_add_f32_e32 v4, 0, v4
	s_add_i32 s87, s83, -4
	v_add_f32_e32 v251, v16, v4
	v_cmp_gt_u32_e64 s[6:7], 32, v243
	s_mov_b32 s88, 2
	v_lshl_add_u32 v16, v242, 2, s76
	s_movk_i32 s86, 0x2000
	s_mov_b32 s89, 0
	s_mov_b64 s[48:49], s[34:35]
	s_mov_b64 s[50:51], s[30:31]
	v_sub_f32_e32 v146, 0, v247
	v_sub_f32_e32 v147, 0, v247
	v_sub_f32_e32 v148, 0, v247
	v_sub_f32_e32 v149, 0, v247
	v_sub_f32_e32 v150, 0, v247
	v_sub_f32_e32 v151, 0, v247
	v_sub_f32_e32 v152, 0, v247
	v_sub_f32_e32 v153, 0, v247
	v_sub_f32_e32 v154, 0, v247
	v_sub_f32_e32 v155, 0, v247
	v_sub_f32_e32 v156, 0, v247
	v_sub_f32_e32 v157, 0, v247
	v_sub_f32_e32 v158, 0, v247
	v_sub_f32_e32 v159, 0, v247
	v_sub_f32_e32 v160, 0, v247
	v_sub_f32_e32 v161, 0, v247
	v_sub_f32_e32 v82, v82, v247
	v_sub_f32_e32 v83, v83, v247
	v_sub_f32_e32 v84, v84, v247
	v_sub_f32_e32 v85, v85, v247
	v_sub_f32_e32 v86, v86, v247
	v_sub_f32_e32 v87, v87, v247
	v_sub_f32_e32 v88, v88, v247
	v_sub_f32_e32 v89, v89, v247
	v_sub_f32_e32 v90, v90, v247
	v_sub_f32_e32 v91, v91, v247
	v_sub_f32_e32 v92, v92, v247
	v_sub_f32_e32 v93, v93, v247
	v_sub_f32_e32 v94, v94, v247
	v_sub_f32_e32 v95, v95, v247
	v_sub_f32_e32 v96, v96, v247
	v_sub_f32_e32 v97, v97, v247
	v_sub_f32_e32 v98, v98, v247
	v_sub_f32_e32 v99, v99, v247
	v_sub_f32_e32 v100, v100, v247
	v_sub_f32_e32 v101, v101, v247
	v_sub_f32_e32 v102, v102, v247
	v_sub_f32_e32 v103, v103, v247
	v_sub_f32_e32 v104, v104, v247
	v_sub_f32_e32 v105, v105, v247
	v_sub_f32_e32 v106, v106, v247
	v_sub_f32_e32 v107, v107, v247
	v_sub_f32_e32 v108, v108, v247
	v_sub_f32_e32 v109, v109, v247
	v_sub_f32_e32 v110, v110, v247
	v_sub_f32_e32 v111, v111, v247
	v_sub_f32_e32 v112, v112, v247
	v_sub_f32_e32 v113, v113, v247
	v_sub_f32_e32 v178, v178, v247
	s_add_u32 s58, s50, 0xfff40000
	s_addc_u32 s59, s51, -1
	s_add_i32 s4, s86, s80
	s_mov_b32 s5, m0
	s_mov_b32 m0, s4
	s_nop 0
	global_load_lds_dwordx4 v252, s[58:59]
	s_mov_b32 m0, s5
	ds_read_b128 v[164:167], v248
	ds_read_b128 v[168:171], v248 offset:1024
	ds_read_b128 v[172:175], v248 offset:2048
	ds_read_b128 v[236:239], v248 offset:3072
	v_add_u32_e32 v240, s89, v249
	ds_read_b128 v[204:207], v240
	ds_read_b128 v[208:211], v240 offset:512
	ds_read_b128 v[212:215], v240 offset:2048
	ds_read_b128 v[216:219], v240 offset:2560
	ds_read_b128 v[220:223], v240 offset:4096
	ds_read_b128 v[224:227], v240 offset:4608
	ds_read_b128 v[228:231], v240 offset:6144
	ds_read_b128 v[232:235], v240 offset:6656
	s_waitcnt vmcnt(0) lgkmcnt(0)
	s_barrier
	s_branch .LBB0_436

; #define SB() __builtin_amdgcn_sched_barrier(0)
; #define MF32(a,b,c) __builtin_amdgcn_mfma_f32_32x32x16_bf16(a,b,c,0,0,0)
; #define EXP1(x) x=__builtin_amdgcn_exp2f((x)-mh_)
; __device__ __forceinline__ bf16x8 vfrag(lds_cptr vp,int i){ const s16x4 lo=vtr(vp+(i&3)*4096+(i>>2)*1024), hh=vtr(vp+(i&3)*4096+(i>>2)*1024+512); return (bf16x8){lo[0],lo[1],lo[2],lo[3],hh[0],hh[1],hh[2],hh[3]}; }
; __device__ __forceinline__ u32x4 packw(const f32x16&p,int base){ u32x4 w; w[0]=cvtpk_s(p[base],p[base+1]); w[1]=cvtpk_s(p[base+2],p[base+3]); w[2]=cvtpk_s(p[base+4],p[base+5]); w[3]=cvtpk_s(p[base+6],p[base+7]); return w; }
; template<int THRL,bool FIRST> __device__ __forceinline__ void step_main(f32x16&p0,f32x16&p1,f32x16&n0,f32x16&n1,St&S,lds_cptr kpn,lds_cptr qp,lds_cptr vp,float*wsf,int r32,int hi,float&rm){
;     ...
;   bf16x8 ka=KF(0),kb=KF(1),kc=KF(2),kd=KF(3),qa=QF(0),qb=QF(1);
;   decide<THRL,FIRST>(rm,S,wsf,r32,hi);
;   u32x4 pw0,pw1,pw2,pw3; const float mh_=S.mhat; const f32x16 z=f32x16{};
;   SB();
;   n0=MF32(ka,qa,z); ka=KF(4); EXP1(p0[0]);EXP1(p0[1]);EXP1(p0[2]); SB();
;   n1=MF32(kb,qa,z); kb=KF(5); qa=QF(2); EXP1(p0[3]);EXP1(p0[4]);EXP1(p0[5]); SB();
;   n0=MF32(kc,qb,n0);   kc=KF(6); EXP1(p0[6]);EXP1(p0[7]);EXP1(p0[8]); SB();
;   n1=MF32(kd,qb,n1);   kd=KF(7); qb=QF(3); EXP1(p0[9]);EXP1(p0[10]);EXP1(p0[11]); SB();
;   bf16x8 vfa=vfrag(vp,0);
;   n0=MF32(ka,qa,n0);   EXP1(p0[12]);EXP1(p0[13]);EXP1(p0[14]); pw0=packw(p0,0); SB();
;   bf16x8 vfb=vfrag(vp,1);
;   n1=MF32(kb,qa,n1);   EXP1(p0[15]);EXP1(p1[0]);EXP1(p1[1]); SB();
;   bf16x8 vfc=vfrag(vp,2);
;   n0=MF32(kc,qb,n0);   EXP1(p1[2]);EXP1(p1[3]);EXP1(p1[4]); pw1=packw(p0,8); SB();
;   bf16x8 vfd=vfrag(vp,3);
;   n1=MF32(kd,qb,n1);   EXP1(p1[5]);EXP1(p1[6]);EXP1(p1[7]); SB();
;     ...
;   float sa=p0[0]+p0[1];
;     ...
;   PVG(0,pw0,vfa,4, p0[2],p0[3],p0[4],p0[5],   do{EXP1(p1[8]);EXP1(p1[9]);}while(0));
;   PVG(1,pw0,vfb,5, p0[6],p0[7],p0[8],p0[9], do{EXP1(p1[10]);EXP1(p1[11]);}while(0));
;   PVG(2,pw0,vfc,6, p0[10],p0[11],p0[12],p0[13], do{EXP1(p1[12]);EXP1(p1[13]);}while(0));
;   PVG(3,pw0,vfd,7, p0[14],p0[15],p1[0],p1[1],   do{EXP1(p1[14]);EXP1(p1[15]);}while(0));
;   PVG(4,pw1,vfa,8, p1[2],p1[3],p1[4],p1[5],   pw2=packw(p1,0));
;   PVG(5,pw1,vfb,9, p1[6],p1[7],p1[8],p1[9], pw3=packw(p1,8));
;   PVG(6,pw1,vfc,10, p1[10],p1[11],p1[12],p1[13], do{}while(0));
;   PVG(7,pw1,vfd,11, p1[14],p1[15],0.f,0.f, do{}while(0));
.LBB0_435:
	s_add_i32 s4, s89, 0x2000
	s_cmpk_lg_i32 s89, 0x4000
	s_cselect_b32 s86, s4, 0
	s_add_i32 s88, s88, 2
	v_mfma_f32_32x32x16_bf16 v[98:113], v[204:207], v[164:167], v[146:161]
	s_add_i32 s4, s86, s80
	s_add_u32 s58, s50, 0xc0000
	s_addc_u32 s59, s51, 0
	s_mov_b32 s5, m0
	s_mov_b32 m0, s4
	s_nop 0
	global_load_lds_dwordx4 v252, s[58:59]
	s_mov_b32 m0, s5
	v_exp_f32_e32 v130, v130
	v_exp_f32_e32 v131, v131
	v_exp_f32_e32 v132, v132
	v_exp_f32_e32 v133, v133
	v_exp_f32_e32 v134, v134
	v_exp_f32_e32 v135, v135
	v_mfma_f32_32x32x16_bf16 v[82:97], v[208:211], v[164:167], v[146:161]
	s_add_u32 s58, s48, 0xc0000
	s_addc_u32 s59, s49, 0
	s_mov_b32 s4, m0
	s_mov_b32 m0, s78
	s_nop 0
	global_load_lds_dwordx4 v250, s[58:59]
	s_mov_b32 m0, s4
	v_mfma_f32_32x32x16_bf16 v[98:113], v[212:215], v[168:171], v[98:113]
	s_add_u32 s58, s48, 0xc0080
	s_addc_u32 s59, s49, 0
	s_mov_b32 s4, m0
	s_mov_b32 m0, s79
	s_nop 0
	global_load_lds_dwordx4 v250, s[58:59]
	s_mov_b32 m0, s4
	v_exp_f32_e32 v136, v136
	v_exp_f32_e32 v137, v137
	v_exp_f32_e32 v138, v138
	v_mfma_f32_32x32x16_bf16 v[82:97], v[216:219], v[168:171], v[82:97]
	v_exp_f32_e32 v139, v139
	v_exp_f32_e32 v140, v140
	v_exp_f32_e32 v141, v141
	v_mfma_f32_32x32x16_bf16 v[98:113], v[220:223], v[172:175], v[98:113]
	v_exp_f32_e32 v142, v142
	ds_read_b64_tr_b16 v[4:5], v246 offset:40960
	ds_read_b64_tr_b16 v[6:7], v246 offset:41472
	v_exp_f32_e32 v143, v143
	v_exp_f32_e32 v144, v144
	v_cvt_pk_bf16_f32 v8, v130, v131
	v_cvt_pk_bf16_f32 v9, v132, v133
	v_cvt_pk_bf16_f32 v10, v134, v135
	v_cvt_pk_bf16_f32 v11, v136, v137
	v_mfma_f32_32x32x16_bf16 v[82:97], v[224:227], v[172:175], v[82:97]
	ds_read_b64_tr_b16 v[178:179], v246 offset:45056
	ds_read_b64_tr_b16 v[180:181], v246 offset:45568
	v_exp_f32_e32 v145, v145
	v_exp_f32_e32 v114, v114
	v_exp_f32_e32 v115, v115
	v_mfma_f32_32x32x16_bf16 v[98:113], v[228:231], v[236:239], v[98:113]
	ds_read_b64_tr_b16 v[182:183], v246 offset:49152
	ds_read_b64_tr_b16 v[184:185], v246 offset:49664
	v_exp_f32_e32 v116, v116
	v_exp_f32_e32 v117, v117
	v_exp_f32_e32 v118, v118
	v_cvt_pk_bf16_f32 v186, v138, v139
	v_cvt_pk_bf16_f32 v187, v140, v141
	v_cvt_pk_bf16_f32 v188, v142, v143
	v_cvt_pk_bf16_f32 v189, v144, v145
	v_mfma_f32_32x32x16_bf16 v[82:97], v[232:235], v[236:239], v[82:97]
	v_add_u32_e32 v240, s89, v249
	ds_read_b64_tr_b16 v[190:191], v246 offset:53248
	ds_read_b64_tr_b16 v[192:193], v246 offset:53760
	v_exp_f32_e32 v119, v119
	v_exp_f32_e32 v120, v120
	v_exp_f32_e32 v121, v121
	s_waitcnt lgkmcnt(6)
	v_mfma_f32_32x32x16_bf16 v[18:33], v[8:11], v[4:7], v[18:33]
	ds_read_b64_tr_b16 v[12:13], v246 offset:41984
	ds_read_b64_tr_b16 v[14:15], v246 offset:42496
	ds_read_b128 v[204:207], v240
	v_add_f32_e32 v194, v130, v131
	v_exp_f32_e32 v122, v122
	v_exp_f32_e32 v123, v123
	v_add_f32_e32 v194, v132, v194
	v_add_f32_e32 v4, v133, v194
	v_add_f32_e32 v4, v134, v4
	v_add_f32_e32 v194, v135, v4
	s_waitcnt lgkmcnt(7)
	v_mfma_f32_32x32x16_bf16 v[34:49], v[8:11], v[178:181], v[34:49]
	ds_read_b64_tr_b16 v[4:5], v246 offset:46080
	ds_read_b64_tr_b16 v[6:7], v246 offset:46592
	ds_read_b128 v[208:211], v240 offset:512
	v_exp_f32_e32 v124, v124
	v_exp_f32_e32 v125, v125
	v_add_f32_e32 v194, v136, v194
	v_add_f32_e32 v178, v137, v194
	v_add_f32_e32 v178, v138, v178
	v_add_f32_e32 v194, v139, v178
	s_waitcnt lgkmcnt(8)
	v_mfma_f32_32x32x16_bf16 v[50:65], v[8:11], v[182:185], v[50:65]
	ds_read_b64_tr_b16 v[178:179], v246 offset:50176
	ds_read_b64_tr_b16 v[180:181], v246 offset:50688
	ds_read_b128 v[212:215], v240 offset:2048
	v_exp_f32_e32 v126, v126
	v_exp_f32_e32 v127, v127
	v_add_f32_e32 v194, v140, v194
	v_add_f32_e32 v182, v141, v194
	v_add_f32_e32 v182, v142, v182
	v_add_f32_e32 v194, v143, v182
	s_waitcnt lgkmcnt(9)
	v_mfma_f32_32x32x16_bf16 v[66:81], v[8:11], v[190:193], v[66:81]
	ds_read_b64_tr_b16 v[182:183], v246 offset:54272
	ds_read_b64_tr_b16 v[184:185], v246 offset:54784
	ds_read_b128 v[216:219], v240 offset:2560
	v_exp_f32_e32 v128, v128
	v_exp_f32_e32 v129, v129
	v_add_f32_e32 v194, v144, v194
	v_add_f32_e32 v8, v145, v194
	v_add_f32_e32 v8, v114, v8
	v_add_f32_e32 v190, v115, v8
	s_waitcnt lgkmcnt(10)
	v_mfma_f32_32x32x16_bf16 v[18:33], v[186:189], v[12:15], v[18:33]
	ds_read_b64_tr_b16 v[8:9], v246 offset:43008
	ds_read_b64_tr_b16 v[10:11], v246 offset:43520
	ds_read_b128 v[220:223], v240 offset:4096
	v_add_f32_e32 v190, v116, v190
	v_add_f32_e32 v190, v117, v190
	v_add_f32_e32 v190, v118, v190
	v_add_f32_e32 v194, v119, v190
	v_cvt_pk_bf16_f32 v12, v114, v115
	v_cvt_pk_bf16_f32 v13, v116, v117
	v_cvt_pk_bf16_f32 v14, v118, v119
	v_cvt_pk_bf16_f32 v15, v120, v121
	s_waitcnt lgkmcnt(10)
	v_mfma_f32_32x32x16_bf16 v[34:49], v[186:189], v[4:7], v[34:49]
	ds_read_b64_tr_b16 v[190:191], v246 offset:47104
	ds_read_b64_tr_b16 v[192:193], v246 offset:47616
	ds_read_b128 v[224:227], v240 offset:4608
	v_add_f32_e32 v194, v120, v194
	v_add_f32_e32 v194, v121, v194
	v_add_f32_e32 v194, v122, v194
	v_add_f32_e32 v198, v123, v194
	v_cvt_pk_bf16_f32 v4, v122, v123
	v_cvt_pk_bf16_f32 v5, v124, v125
	v_cvt_pk_bf16_f32 v6, v126, v127
	v_cvt_pk_bf16_f32 v7, v128, v129
	s_waitcnt lgkmcnt(10)
	v_mfma_f32_32x32x16_bf16 v[50:65], v[186:189], v[178:181], v[50:65]
	ds_read_b64_tr_b16 v[194:195], v246 offset:51200
	ds_read_b64_tr_b16 v[196:197], v246 offset:51712
	ds_read_b128 v[228:231], v240 offset:6144
	v_add_f32_e32 v198, v124, v198
	v_add_f32_e32 v198, v125, v198
	v_add_f32_e32 v198, v126, v198
	v_add_f32_e32 v198, v127, v198
	s_waitcnt lgkmcnt(10)
; __device__ __forceinline__ int crow(int r,int hi){return (r&3)+8*(r>>2)+4*hi;}
; __device__ __forceinline__ float max3f(float a,float b,float c){float r;asm("v_max3_f32 %0, %1, %2, %3":"=v"(r):"v"(a),"v"(b),"v"(c));return r;}
; __device__ __forceinline__ float max2f(float a,float b){float r;asm("v_max_f32_e32 %0, %1, %2":"=v"(r):"v"(a),"v"(b));return r;}
;   #define PVG(i,PW,VF,NEXTI,X0,X1,Y0,Y1,EXTRA) do{ S.o[(i)&3]=MF32(__builtin_bit_cast(bf16x8,PW),VF,S.o[(i)&3]); if((NEXTI)<16){ VF=vfrag(vp,(NEXTI)<16?(NEXTI):0); } sa+=X0; sa+=X1; sa+=Y0; sa+=Y1; EXTRA; SB(); }while(0)
; template<int THRL,bool FIRST> __device__ __forceinline__ void decide(float rm,St&S,float*wsf,int r32,int hi){
;     ...
;   else if(__any(rm-S.mhat>(float)THRL)){
;     const float dl=__builtin_fmaxf(rm-S.mhat,0.f); S.mhat+=dl;
;     const float f=__builtin_amdgcn_exp2f(-dl); S.l_reg*=f; if(hi==0)wsf[r32]=f;
;     asm volatile("s_waitcnt lgkmcnt(0)":::"memory");
;     #pragma unroll
;     for(int r=0;r<16;++r){ const float fr=wsf[crow(r,hi)];
;       #pragma unroll
;       for(int d=0;d<4;++d)S.o[d][r]*=fr; }
; template<int THRL,bool FIRST> __device__ __forceinline__ void step_main(f32x16&p0,f32x16&p1,f32x16&n0,f32x16&n1,St&S,lds_cptr kpn,lds_cptr qp,lds_cptr vp,float*wsf,int r32,int hi,float&rm){
;     ...
;   float ma,mb;
;     ...
;   PVG(8,pw2,vfa,12,0.f,0.f,0.f,0.f, do{ma=max3f(n0[0],n0[1],n1[0]);mb=max3f(n0[2],n0[3],n1[1]);PINAB();}while(0));
;   PVG(9,pw2,vfb,13,0.f,0.f,0.f,0.f, do{ma=max3f(ma,n1[2],n1[3]);mb=max3f(mb,n0[4],n0[5]);PINAB();}while(0));
;   PVG(10,pw2,vfc,14,0.f,0.f,0.f,0.f, do{ma=max3f(ma,n0[6],n0[7]);mb=max3f(mb,n1[4],n1[5]);PINAB();}while(0));
;   PVG(11,pw2,vfd,15,0.f,0.f,0.f,0.f, do{ma=max3f(ma,n1[6],n1[7]);mb=max3f(mb,n0[8],n0[9]);PINAB();}while(0));
;   PVG(12,pw3,vfa,16,0.f,0.f,0.f,0.f, do{ma=max3f(ma,n0[10],n0[11]);mb=max3f(mb,n1[8],n1[9]);PINAB();}while(0));
;   PVG(13,pw3,vfb,16,0.f,0.f,0.f,0.f, do{ma=max3f(ma,n1[10],n1[11]);mb=max3f(mb,n0[12],n0[13]);PINAB();}while(0));
;   PVG(14,pw3,vfc,16,0.f,0.f,0.f,0.f, do{ma=max3f(ma,n0[14],n0[15]);mb=max3f(mb,n1[12],n1[13]);PINAB();}while(0));
;   PVG(15,pw3,vfd,16,0.f,0.f,0.f,0.f, do{ma=max3f(ma,n1[14],n1[15]);ma=max2f(ma,mb);PINAB();}while(0));
;     ...
;   { auto rr=__builtin_amdgcn_permlane32_swap(__float_as_uint(ma),__float_as_uint(ma),false,false); rm=max2f(__uint_as_float(rr[0]),__uint_as_float(rr[1])); }
	v_mfma_f32_32x32x16_bf16 v[66:81], v[186:189], v[182:185], v[66:81]
	ds_read_b64_tr_b16 v[178:179], v246 offset:55296
	ds_read_b64_tr_b16 v[180:181], v246 offset:55808
	ds_read_b128 v[232:235], v240 offset:6656
	v_add_f32_e32 v198, v128, v198
	v_add_f32_e32 v198, v129, v198
	v_add_f32_e32 v198, 0, v198
	s_waitcnt lgkmcnt(10)
	v_mfma_f32_32x32x16_bf16 v[18:33], v[12:15], v[8:11], v[18:33]
	ds_read_b64_tr_b16 v[182:183], v246 offset:44032
	ds_read_b64_tr_b16 v[184:185], v246 offset:44544
	v_max3_f32 v186, v98, v99, v82
	v_max3_f32 v187, v100, v101, v83
	s_nop 0
	s_waitcnt lgkmcnt(9)
	v_mfma_f32_32x32x16_bf16 v[34:49], v[12:15], v[190:193], v[34:49]
	ds_read_b64_tr_b16 v[8:9], v246 offset:48128
	ds_read_b64_tr_b16 v[10:11], v246 offset:48640
	v_max3_f32 v199, v186, v84, v85
	v_max3_f32 v200, v187, v102, v103
	s_nop 0
	s_waitcnt lgkmcnt(8)
	v_mfma_f32_32x32x16_bf16 v[50:65], v[12:15], v[194:197], v[50:65]
	ds_read_b64_tr_b16 v[186:187], v246 offset:52224
	ds_read_b64_tr_b16 v[188:189], v246 offset:52736
	v_max3_f32 v199, v199, v104, v105
	v_max3_f32 v200, v200, v86, v87
	s_nop 0
	s_waitcnt lgkmcnt(7)
	v_mfma_f32_32x32x16_bf16 v[66:81], v[12:15], v[178:181], v[66:81]
	ds_read_b64_tr_b16 v[190:191], v246 offset:56320
	ds_read_b64_tr_b16 v[192:193], v246 offset:56832
	v_max3_f32 v194, v199, v88, v89
	v_max3_f32 v195, v200, v106, v107
	s_nop 0
	s_waitcnt lgkmcnt(6)
	v_mfma_f32_32x32x16_bf16 v[18:33], v[4:7], v[182:185], v[18:33]
	v_max3_f32 v12, v194, v108, v109
	v_max3_f32 v13, v195, v90, v91
	s_nop 0
	s_waitcnt lgkmcnt(4)
	v_mfma_f32_32x32x16_bf16 v[34:49], v[4:7], v[8:11], v[34:49]
	v_max3_f32 v12, v12, v92, v93
	v_max3_f32 v13, v13, v110, v111
	s_nop 0
	s_waitcnt lgkmcnt(2)
	v_mfma_f32_32x32x16_bf16 v[50:65], v[4:7], v[186:189], v[50:65]
	v_max3_f32 v8, v12, v112, v113
	v_max3_f32 v9, v13, v94, v95
	s_nop 0
	s_waitcnt lgkmcnt(0)
	v_mfma_f32_32x32x16_bf16 v[66:81], v[4:7], v[190:193], v[66:81]
	v_max3_f32 v8, v8, v96, v97
	s_nop 0
	v_max_f32_e32 v8, v8, v9
	s_nop 0
	s_add_u32 s50, s50, 0x180000
	s_addc_u32 s51, s51, 0
	s_add_u32 s48, s48, 0x180000
	s_waitcnt vmcnt(0) lgkmcnt(0)
	s_barrier
	s_addc_u32 s49, s49, 0
	v_mov_b32_e32 v4, v8
	v_add_f32_e32 v251, v17, v198
	s_cmp_lt_u32 s88, s87
	v_permlane32_swap_b32_e32 v8, v4
	v_max_f32_e32 v178, v8, v4
	s_cbranch_scc0 .LBB0_443
.LBB0_436:
	v_mov_b32_e32 v126, v178
	v_cmp_lt_f32_e32 vcc, s67, v126
	s_cbranch_vccz .LBB0_440
	v_max_f32_e32 v126, v126, v126
	v_max_f32_e32 v126, 0, v126
	v_exp_f32_e64 v127, -v126
	s_and_saveexec_b64 s[58:59], s[6:7]
	ds_write_b32 v16, v127
	s_or_b64 exec, exec, s[58:59]
	s_waitcnt lgkmcnt(0)
	v_add_u32_e32 v140, s76, v2
	ds_read_b128 v[128:131], v140 offset:64
	ds_read_b128 v[132:135], v140 offset:96
	ds_read_b128 v[136:139], v140
	ds_read_b128 v[140:143], v140 offset:32
	v_add_f32_e32 v247, v247, v126
	v_sub_f32_e32 v146, v146, v126
	v_sub_f32_e32 v147, v147, v126
	v_sub_f32_e32 v148, v148, v126
	v_sub_f32_e32 v149, v149, v126
	v_sub_f32_e32 v150, v150, v126
	v_sub_f32_e32 v151, v151, v126
	v_sub_f32_e32 v152, v152, v126
	v_sub_f32_e32 v153, v153, v126
	v_sub_f32_e32 v154, v154, v126
	v_sub_f32_e32 v155, v155, v126
	v_sub_f32_e32 v156, v156, v126
	v_sub_f32_e32 v157, v157, v126
	v_sub_f32_e32 v158, v158, v126
	v_sub_f32_e32 v159, v159, v126
	v_sub_f32_e32 v160, v160, v126
	v_sub_f32_e32 v161, v161, v126
	v_sub_f32_e32 v82, v82, v126
	v_sub_f32_e32 v83, v83, v126
	v_sub_f32_e32 v84, v84, v126
	v_sub_f32_e32 v85, v85, v126
	v_sub_f32_e32 v86, v86, v126
	v_sub_f32_e32 v87, v87, v126
	v_sub_f32_e32 v88, v88, v126
	v_sub_f32_e32 v89, v89, v126
	v_sub_f32_e32 v90, v90, v126
	v_sub_f32_e32 v91, v91, v126
	v_sub_f32_e32 v92, v92, v126
	v_sub_f32_e32 v93, v93, v126
	v_sub_f32_e32 v94, v94, v126
	v_sub_f32_e32 v95, v95, v126
	v_sub_f32_e32 v96, v96, v126
	v_sub_f32_e32 v97, v97, v126
	v_sub_f32_e32 v98, v98, v126
	v_sub_f32_e32 v99, v99, v126
	v_sub_f32_e32 v100, v100, v126
	v_sub_f32_e32 v101, v101, v126
	v_sub_f32_e32 v102, v102, v126
	v_sub_f32_e32 v103, v103, v126
	v_sub_f32_e32 v104, v104, v126
	v_sub_f32_e32 v105, v105, v126
	v_sub_f32_e32 v106, v106, v126
	v_sub_f32_e32 v107, v107, v126
	v_sub_f32_e32 v108, v108, v126
	v_sub_f32_e32 v109, v109, v126
	v_sub_f32_e32 v110, v110, v126
	v_sub_f32_e32 v111, v111, v126
	v_sub_f32_e32 v112, v112, v126
	v_sub_f32_e32 v113, v113, v126
	v_mul_f32_e32 v251, v251, v127
	s_waitcnt lgkmcnt(2)
	v_pk_mul_f32 v[30:31], v[30:31], v[132:133]
	v_pk_mul_f32 v[26:27], v[26:27], v[128:129]
	s_waitcnt lgkmcnt(0)
	v_pk_mul_f32 v[22:23], v[22:23], v[140:141]
	v_pk_mul_f32 v[32:33], v[32:33], v[134:135]
	v_pk_mul_f32 v[28:29], v[28:29], v[130:131]
	v_pk_mul_f32 v[24:25], v[24:25], v[142:143]
	v_pk_mul_f32 v[20:21], v[20:21], v[138:139]
	v_pk_mul_f32 v[18:19], v[18:19], v[136:137]
	v_pk_mul_f32 v[46:47], v[46:47], v[132:133]
	v_pk_mul_f32 v[42:43], v[42:43], v[128:129]
	v_pk_mul_f32 v[38:39], v[38:39], v[140:141]
	v_pk_mul_f32 v[48:49], v[48:49], v[134:135]
	v_pk_mul_f32 v[44:45], v[44:45], v[130:131]
	v_pk_mul_f32 v[40:41], v[40:41], v[142:143]
	v_pk_mul_f32 v[36:37], v[36:37], v[138:139]
	v_pk_mul_f32 v[34:35], v[34:35], v[136:137]
	v_pk_mul_f32 v[62:63], v[62:63], v[132:133]
	v_pk_mul_f32 v[58:59], v[58:59], v[128:129]
	v_pk_mul_f32 v[54:55], v[54:55], v[140:141]
	v_pk_mul_f32 v[64:65], v[64:65], v[134:135]
	v_pk_mul_f32 v[60:61], v[60:61], v[130:131]
	v_pk_mul_f32 v[56:57], v[56:57], v[142:143]
	v_pk_mul_f32 v[52:53], v[52:53], v[138:139]
	v_pk_mul_f32 v[50:51], v[50:51], v[136:137]
	v_pk_mul_f32 v[78:79], v[78:79], v[132:133]
	v_pk_mul_f32 v[74:75], v[74:75], v[128:129]
	v_pk_mul_f32 v[70:71], v[70:71], v[140:141]
	v_pk_mul_f32 v[80:81], v[80:81], v[134:135]
	v_pk_mul_f32 v[76:77], v[76:77], v[130:131]
	v_pk_mul_f32 v[72:73], v[72:73], v[142:143]
	v_pk_mul_f32 v[68:69], v[68:69], v[138:139]
	v_pk_mul_f32 v[66:67], v[66:67], v[136:137]
; #define SB() __builtin_amdgcn_sched_barrier(0)
; #define MF32(a,b,c) __builtin_amdgcn_mfma_f32_32x32x16_bf16(a,b,c,0,0,0)
; #define EXP1(x) x=__builtin_amdgcn_exp2f((x)-mh_)
; __device__ __forceinline__ bf16x8 vfrag(lds_cptr vp,int i){ const s16x4 lo=vtr(vp+(i&3)*4096+(i>>2)*1024), hh=vtr(vp+(i&3)*4096+(i>>2)*1024+512); return (bf16x8){lo[0],lo[1],lo[2],lo[3],hh[0],hh[1],hh[2],hh[3]}; }
; __device__ __forceinline__ u32x4 packw(const f32x16&p,int base){ u32x4 w; w[0]=cvtpk_s(p[base],p[base+1]); w[1]=cvtpk_s(p[base+2],p[base+3]); w[2]=cvtpk_s(p[base+4],p[base+5]); w[3]=cvtpk_s(p[base+6],p[base+7]); return w; }
; template<int THRL,bool FIRST> __device__ __forceinline__ void step_main(f32x16&p0,f32x16&p1,f32x16&n0,f32x16&n1,St&S,lds_cptr kpn,lds_cptr qp,lds_cptr vp,float*wsf,int r32,int hi,float&rm){
;     ...
;   bf16x8 ka=KF(0),kb=KF(1),kc=KF(2),kd=KF(3),qa=QF(0),qb=QF(1);
;   decide<THRL,FIRST>(rm,S,wsf,r32,hi);
;   u32x4 pw0,pw1,pw2,pw3; const float mh_=S.mhat; const f32x16 z=f32x16{};
;   SB();
;   n0=MF32(ka,qa,z); ka=KF(4); EXP1(p0[0]);EXP1(p0[1]);EXP1(p0[2]); SB();
;   n1=MF32(kb,qa,z); kb=KF(5); qa=QF(2); EXP1(p0[3]);EXP1(p0[4]);EXP1(p0[5]); SB();
;   n0=MF32(kc,qb,n0);   kc=KF(6); EXP1(p0[6]);EXP1(p0[7]);EXP1(p0[8]); SB();
;   n1=MF32(kd,qb,n1);   kd=KF(7); qb=QF(3); EXP1(p0[9]);EXP1(p0[10]);EXP1(p0[11]); SB();
;   bf16x8 vfa=vfrag(vp,0);
;   n0=MF32(ka,qa,n0);   EXP1(p0[12]);EXP1(p0[13]);EXP1(p0[14]); pw0=packw(p0,0); SB();
;   bf16x8 vfb=vfrag(vp,1);
;   n1=MF32(kb,qa,n1);   EXP1(p0[15]);EXP1(p1[0]);EXP1(p1[1]); SB();
;   bf16x8 vfc=vfrag(vp,2);
;   n0=MF32(kc,qb,n0);   EXP1(p1[2]);EXP1(p1[3]);EXP1(p1[4]); pw1=packw(p0,8); SB();
;   bf16x8 vfd=vfrag(vp,3);
;   n1=MF32(kd,qb,n1);   EXP1(p1[5]);EXP1(p1[6]);EXP1(p1[7]); SB();
;     ...
;   float sa=p0[0]+p0[1];
;     ...
;   PVG(0,pw0,vfa,4, p0[2],p0[3],p0[4],p0[5],   do{EXP1(p1[8]);EXP1(p1[9]);}while(0));
;   PVG(1,pw0,vfb,5, p0[6],p0[7],p0[8],p0[9], do{EXP1(p1[10]);EXP1(p1[11]);}while(0));
;   PVG(2,pw0,vfc,6, p0[10],p0[11],p0[12],p0[13], do{EXP1(p1[12]);EXP1(p1[13]);}while(0));
;   PVG(3,pw0,vfd,7, p0[14],p0[15],p1[0],p1[1],   do{EXP1(p1[14]);EXP1(p1[15]);}while(0));
;   PVG(4,pw1,vfa,8, p1[2],p1[3],p1[4],p1[5],   pw2=packw(p1,0));
;   PVG(5,pw1,vfb,9, p1[6],p1[7],p1[8],p1[9], pw3=packw(p1,8));
;   PVG(6,pw1,vfc,10, p1[10],p1[11],p1[12],p1[13], do{}while(0));
;   PVG(7,pw1,vfd,11, p1[14],p1[15],0.f,0.f, do{}while(0));
.LBB0_440:
	s_add_i32 s4, s86, 0x2000
	s_cmpk_lg_i32 s86, 0x4000
	s_cselect_b32 s89, s4, 0
	v_mfma_f32_32x32x16_bf16 v[130:145], v[204:207], v[164:167], v[146:161]
	s_add_i32 s4, s89, s80
	s_mov_b32 s5, m0
	s_mov_b32 m0, s4
	s_nop 0
	global_load_lds_dwordx4 v252, s[50:51]
	s_mov_b32 m0, s5
	v_exp_f32_e32 v190, v98
	v_exp_f32_e32 v191, v99
	v_exp_f32_e32 v192, v100
	v_mfma_f32_32x32x16_bf16 v[114:129], v[208:211], v[164:167], v[146:161]
	s_mov_b32 s4, m0
	s_mov_b32 m0, s77
	s_nop 0
	global_load_lds_dwordx4 v250, s[48:49]
	s_mov_b32 m0, s4
	v_exp_f32_e32 v193, v101
	v_exp_f32_e32 v194, v102
	v_exp_f32_e32 v195, v103
	v_mfma_f32_32x32x16_bf16 v[130:145], v[212:215], v[168:171], v[130:145]
	s_add_u32 s58, s48, 0x80
	s_addc_u32 s59, s49, 0
	s_mov_b32 s4, m0
	s_mov_b32 m0, s39
	s_nop 0
	global_load_lds_dwordx4 v250, s[58:59]
	s_mov_b32 m0, s4
	v_exp_f32_e32 v196, v104
	v_exp_f32_e32 v197, v105
	v_exp_f32_e32 v198, v106
	v_mfma_f32_32x32x16_bf16 v[114:129], v[216:219], v[168:171], v[114:129]
	v_exp_f32_e32 v17, v107
	v_exp_f32_e32 v199, v108
	v_exp_f32_e32 v200, v109
	v_mfma_f32_32x32x16_bf16 v[130:145], v[220:223], v[172:175], v[130:145]
	v_exp_f32_e32 v201, v110
	ds_read_b64_tr_b16 v[4:5], v246 offset:24576
	ds_read_b64_tr_b16 v[6:7], v246 offset:25088
	v_exp_f32_e32 v202, v111
	v_exp_f32_e32 v178, v112
	v_cvt_pk_bf16_f32 v8, v190, v191
	v_cvt_pk_bf16_f32 v9, v192, v193
	v_cvt_pk_bf16_f32 v10, v194, v195
	v_cvt_pk_bf16_f32 v11, v196, v197
	v_mfma_f32_32x32x16_bf16 v[114:129], v[224:227], v[172:175], v[114:129]
	ds_read_b64_tr_b16 v[106:107], v246 offset:28672
	ds_read_b64_tr_b16 v[108:109], v246 offset:29184
	v_exp_f32_e32 v180, v82
	v_exp_f32_e32 v179, v113
	v_exp_f32_e32 v181, v83
	v_mfma_f32_32x32x16_bf16 v[130:145], v[228:231], v[236:239], v[130:145]
	ds_read_b64_tr_b16 v[110:111], v246 offset:32768
	ds_read_b64_tr_b16 v[112:113], v246 offset:33280
	v_exp_f32_e32 v182, v84
	v_exp_f32_e32 v183, v85
	v_exp_f32_e32 v184, v86
	v_cvt_pk_bf16_f32 v82, v198, v17
	v_cvt_pk_bf16_f32 v83, v199, v200
	v_cvt_pk_bf16_f32 v84, v201, v202
	v_cvt_pk_bf16_f32 v85, v178, v179
	v_mfma_f32_32x32x16_bf16 v[114:129], v[232:235], v[236:239], v[114:129]
	v_add_u32_e32 v240, s86, v249
	ds_read_b64_tr_b16 v[98:99], v246 offset:36864
	ds_read_b64_tr_b16 v[100:101], v246 offset:37376
	v_exp_f32_e32 v185, v87
	v_exp_f32_e32 v186, v88
	v_exp_f32_e32 v187, v89
	s_waitcnt lgkmcnt(6)
	v_mfma_f32_32x32x16_bf16 v[18:33], v[8:11], v[4:7], v[18:33]
	ds_read_b128 v[204:207], v240
	v_add_f32_e32 v86, v190, v191
	ds_read_b64_tr_b16 v[12:13], v246 offset:25600
	ds_read_b64_tr_b16 v[14:15], v246 offset:26112
	v_add_f32_e32 v86, v192, v86
	v_exp_f32_e32 v103, v91
	v_add_f32_e32 v4, v193, v86
	v_add_f32_e32 v4, v194, v4
	v_add_f32_e32 v86, v195, v4
	v_exp_f32_e32 v102, v90
	s_waitcnt lgkmcnt(7)
	v_mfma_f32_32x32x16_bf16 v[34:49], v[8:11], v[106:109], v[34:49]
	ds_read_b64_tr_b16 v[4:5], v246 offset:29696
	ds_read_b64_tr_b16 v[6:7], v246 offset:30208
	ds_read_b128 v[208:211], v240 offset:512
	v_add_f32_e32 v86, v196, v86
	v_add_f32_e32 v86, v197, v86
	v_add_f32_e32 v86, v198, v86
	v_exp_f32_e32 v104, v92
	v_add_f32_e32 v17, v17, v86
	v_exp_f32_e32 v105, v93
	s_waitcnt lgkmcnt(8)
	v_mfma_f32_32x32x16_bf16 v[50:65], v[8:11], v[110:113], v[50:65]
	ds_read_b64_tr_b16 v[86:87], v246 offset:33792
	ds_read_b64_tr_b16 v[88:89], v246 offset:34304
	ds_read_b128 v[212:215], v240 offset:2048
	v_add_f32_e32 v17, v199, v17
	v_add_f32_e32 v17, v200, v17
	v_add_f32_e32 v17, v201, v17
	v_exp_f32_e32 v106, v94
	v_add_f32_e32 v17, v202, v17
	v_exp_f32_e32 v107, v95
	s_waitcnt lgkmcnt(9)
	v_mfma_f32_32x32x16_bf16 v[66:81], v[8:11], v[98:101], v[66:81]
	ds_read_b64_tr_b16 v[90:91], v246 offset:37888
	ds_read_b64_tr_b16 v[92:93], v246 offset:38400
	ds_read_b128 v[216:219], v240 offset:2560
	v_add_f32_e32 v17, v178, v17
	v_add_f32_e32 v8, v179, v17
	v_add_f32_e32 v8, v180, v8
	v_exp_f32_e32 v108, v96
	v_add_f32_e32 v17, v181, v8
	v_exp_f32_e32 v109, v97
	s_waitcnt lgkmcnt(9)
; __device__ __forceinline__ float max3f(float a,float b,float c){float r;asm("v_max3_f32 %0, %1, %2, %3":"=v"(r):"v"(a),"v"(b),"v"(c));return r;}
; __device__ __forceinline__ float max2f(float a,float b){float r;asm("v_max_f32_e32 %0, %1, %2":"=v"(r):"v"(a),"v"(b));return r;}
; #define EXP1(x) x=__builtin_amdgcn_exp2f((x)-mh_)
;   #define PINAB() asm volatile("":"+v"(ma),"+v"(mb))
; template<int THRL,bool FIRST> __device__ __forceinline__ void step_main(f32x16&p0,f32x16&p1,f32x16&n0,f32x16&n1,St&S,lds_cptr kpn,lds_cptr qp,lds_cptr vp,float*wsf,int r32,int hi,float&rm){
;     ...
;   PVG(0,pw0,vfa,4, p0[2],p0[3],p0[4],p0[5],   do{EXP1(p1[8]);EXP1(p1[9]);}while(0));
;   PVG(1,pw0,vfb,5, p0[6],p0[7],p0[8],p0[9], do{EXP1(p1[10]);EXP1(p1[11]);}while(0));
;   PVG(2,pw0,vfc,6, p0[10],p0[11],p0[12],p0[13], do{EXP1(p1[12]);EXP1(p1[13]);}while(0));
;   PVG(3,pw0,vfd,7, p0[14],p0[15],p1[0],p1[1],   do{EXP1(p1[14]);EXP1(p1[15]);}while(0));
;   PVG(4,pw1,vfa,8, p1[2],p1[3],p1[4],p1[5],   pw2=packw(p1,0));
;   PVG(5,pw1,vfb,9, p1[6],p1[7],p1[8],p1[9], pw3=packw(p1,8));
;   PVG(6,pw1,vfc,10, p1[10],p1[11],p1[12],p1[13], do{}while(0));
;   PVG(7,pw1,vfd,11, p1[14],p1[15],0.f,0.f, do{}while(0));
;   float ma,mb;
;     ...
;   PVG(8,pw2,vfa,12,0.f,0.f,0.f,0.f, do{ma=max3f(n0[0],n0[1],n1[0]);mb=max3f(n0[2],n0[3],n1[1]);PINAB();}while(0));
;   PVG(9,pw2,vfb,13,0.f,0.f,0.f,0.f, do{ma=max3f(ma,n1[2],n1[3]);mb=max3f(mb,n0[4],n0[5]);PINAB();}while(0));
;   PVG(10,pw2,vfc,14,0.f,0.f,0.f,0.f, do{ma=max3f(ma,n0[6],n0[7]);mb=max3f(mb,n1[4],n1[5]);PINAB();}while(0));
;   PVG(11,pw2,vfd,15,0.f,0.f,0.f,0.f, do{ma=max3f(ma,n1[6],n1[7]);mb=max3f(mb,n0[8],n0[9]);PINAB();}while(0));
;   PVG(12,pw3,vfa,16,0.f,0.f,0.f,0.f, do{ma=max3f(ma,n0[10],n0[11]);mb=max3f(mb,n1[8],n1[9]);PINAB();}while(0));
;   PVG(13,pw3,vfb,16,0.f,0.f,0.f,0.f, do{ma=max3f(ma,n1[10],n1[11]);mb=max3f(mb,n0[12],n0[13]);PINAB();}while(0));
;   PVG(14,pw3,vfc,16,0.f,0.f,0.f,0.f, do{ma=max3f(ma,n0[14],n0[15]);mb=max3f(mb,n1[12],n1[13]);PINAB();}while(0));
;   PVG(15,pw3,vfd,16,0.f,0.f,0.f,0.f, do{ma=max3f(ma,n1[14],n1[15]);ma=max2f(ma,mb);PINAB();}while(0));
;     ...
;   { auto rr=__builtin_amdgcn_permlane32_swap(__float_as_uint(ma),__float_as_uint(ma),false,false); rm=max2f(__uint_as_float(rr[0]),__uint_as_float(rr[1])); }
;     ...
;   S.l_reg+=sa;
	v_mfma_f32_32x32x16_bf16 v[18:33], v[82:85], v[12:15], v[18:33]
	ds_read_b64_tr_b16 v[8:9], v246 offset:26624
	ds_read_b64_tr_b16 v[10:11], v246 offset:27136
	ds_read_b128 v[220:223], v240 offset:4096
	v_add_f32_e32 v17, v182, v17
	v_add_f32_e32 v17, v183, v17
	v_add_f32_e32 v17, v184, v17
	v_add_f32_e32 v17, v185, v17
	v_cvt_pk_bf16_f32 v12, v180, v181
	v_cvt_pk_bf16_f32 v13, v182, v183
	v_cvt_pk_bf16_f32 v14, v184, v185
	v_cvt_pk_bf16_f32 v15, v186, v187
	s_waitcnt lgkmcnt(10)
	v_mfma_f32_32x32x16_bf16 v[34:49], v[82:85], v[4:7], v[34:49]
	ds_read_b64_tr_b16 v[94:95], v246 offset:30720
	ds_read_b64_tr_b16 v[96:97], v246 offset:31232
	ds_read_b128 v[224:227], v240 offset:4608
	v_add_f32_e32 v17, v186, v17
	v_add_f32_e32 v17, v187, v17
	v_add_f32_e32 v17, v102, v17
	v_add_f32_e32 v17, v103, v17
	v_cvt_pk_bf16_f32 v4, v102, v103
	v_cvt_pk_bf16_f32 v5, v104, v105
	v_cvt_pk_bf16_f32 v6, v106, v107
	v_cvt_pk_bf16_f32 v7, v108, v109
	s_waitcnt lgkmcnt(10)
	v_mfma_f32_32x32x16_bf16 v[50:65], v[82:85], v[86:89], v[50:65]
	ds_read_b64_tr_b16 v[98:99], v246 offset:34816
	ds_read_b64_tr_b16 v[100:101], v246 offset:35328
	ds_read_b128 v[228:231], v240 offset:6144
	v_add_f32_e32 v17, v104, v17
	v_add_f32_e32 v17, v105, v17
	v_add_f32_e32 v17, v106, v17
	v_add_f32_e32 v17, v107, v17
	s_waitcnt lgkmcnt(10)
	v_mfma_f32_32x32x16_bf16 v[66:81], v[82:85], v[90:93], v[66:81]
	ds_read_b64_tr_b16 v[86:87], v246 offset:38912
	ds_read_b64_tr_b16 v[88:89], v246 offset:39424
	ds_read_b128 v[232:235], v240 offset:6656
	v_add_f32_e32 v17, v108, v17
	v_add_f32_e32 v17, v109, v17
	v_add_f32_e32 v17, 0, v17
	s_waitcnt lgkmcnt(10)
	v_mfma_f32_32x32x16_bf16 v[18:33], v[12:15], v[8:11], v[18:33]
	ds_read_b64_tr_b16 v[82:83], v246 offset:27648
	ds_read_b64_tr_b16 v[84:85], v246 offset:28160
	v_max3_f32 v90, v130, v131, v114
	v_max3_f32 v91, v132, v133, v115
	s_nop 0
	s_waitcnt lgkmcnt(9)
	v_mfma_f32_32x32x16_bf16 v[34:49], v[12:15], v[94:97], v[34:49]
	ds_read_b64_tr_b16 v[8:9], v246 offset:31744
	ds_read_b64_tr_b16 v[10:11], v246 offset:32256
	v_max3_f32 v102, v90, v116, v117
	v_max3_f32 v103, v91, v134, v135
	s_nop 0
	s_waitcnt lgkmcnt(8)
	v_mfma_f32_32x32x16_bf16 v[50:65], v[12:15], v[98:101], v[50:65]
	ds_read_b64_tr_b16 v[90:91], v246 offset:35840
	ds_read_b64_tr_b16 v[92:93], v246 offset:36352
	v_max3_f32 v102, v102, v136, v137
	v_max3_f32 v103, v103, v118, v119
	s_nop 0
	s_waitcnt lgkmcnt(7)
	v_mfma_f32_32x32x16_bf16 v[66:81], v[12:15], v[86:89], v[66:81]
	ds_read_b64_tr_b16 v[94:95], v246 offset:39936
	ds_read_b64_tr_b16 v[96:97], v246 offset:40448
	v_max3_f32 v98, v102, v120, v121
	v_max3_f32 v99, v103, v138, v139
	s_nop 0
	s_waitcnt lgkmcnt(6)
	v_mfma_f32_32x32x16_bf16 v[18:33], v[4:7], v[82:85], v[18:33]
	v_max3_f32 v12, v98, v140, v141
	v_max3_f32 v13, v99, v122, v123
	s_nop 0
	s_waitcnt lgkmcnt(4)
	v_mfma_f32_32x32x16_bf16 v[34:49], v[4:7], v[8:11], v[34:49]
	v_max3_f32 v12, v12, v124, v125
	v_max3_f32 v13, v13, v142, v143
	s_nop 0
	s_waitcnt lgkmcnt(2)
	v_mfma_f32_32x32x16_bf16 v[50:65], v[4:7], v[90:93], v[50:65]
	v_max3_f32 v8, v12, v144, v145
	v_max3_f32 v9, v13, v126, v127
	s_nop 0
	s_waitcnt lgkmcnt(0)
	v_mfma_f32_32x32x16_bf16 v[66:81], v[4:7], v[94:97], v[66:81]
	v_max3_f32 v8, v8, v128, v129
	s_nop 0
	v_max_f32_e32 v8, v8, v9
	s_nop 0
	v_mov_b32_e32 v162, v8
	v_mov_b32_e32 v163, v8
	s_waitcnt vmcnt(0) lgkmcnt(0)
	s_barrier
	v_permlane32_swap_b32_e32 v162, v163
	v_max_f32_e32 v94, v162, v163
	v_add_f32_e32 v17, v251, v17
	v_cmp_lt_f32_e32 vcc, s67, v94
	s_cbranch_vccz .LBB0_435
	v_max_f32_e32 v94, v94, v94
	v_max_f32_e32 v94, 0, v94
	v_exp_f32_e64 v95, -v94
	s_and_saveexec_b64 s[58:59], s[6:7]
	s_cbranch_execz .LBB0_434
	ds_write_b32 v16, v95
	s_branch .LBB0_434
